# added: QKV-diff epilogue rope-table loads prefetched one pair ahead; grid barrier L1/L2 invalidate issued at arrival instead of after release; redundant invalidate in LN panel sync removed
# speedup vs baseline: 1.0053x; 1.0053x over previous
; __device__ __forceinline__ unsigned xb_ld(unsigned* p)              { return __hip_atomic_load(p, __ATOMIC_RELAXED, __HIP_MEMORY_SCOPE_AGENT); }
; __device__ __forceinline__ unsigned xb_add(unsigned* p, unsigned v) { return __hip_atomic_fetch_add(p, v, __ATOMIC_RELAXED, __HIP_MEMORY_SCOPE_AGENT); }
; #define XB_SPIN(cond, bar) do { unsigned _sp = 0; while (cond) { __builtin_amdgcn_s_sleep(1); \
;     if ((++_sp & 255u) == 0u) { if (xb_ld(&(bar)[XB_TMO])) break; if (_sp > XB_SPIN_CAP) { atomicAdd(&(bar)[XB_TMO], 1u); break; } } } } while (0)
; __device__ __forceinline__ void xcd_barrier(const XcdBarrier& b) {
;     ...
;         const unsigned old = xb_add(&bar[XB_XSUB(b.x)], 1u);
;         const unsigned gen = old / nloc;
;         if (old + 1u == (gen + 1u) * nloc) {
;             __builtin_amdgcn_fence(__ATOMIC_RELEASE, "agent");
;             asm volatile("s_waitcnt vmcnt(0)" ::: "memory");
;             const unsigned og = xb_add(&bar[XB_TOP], 1u);
;             const unsigned tg = og / nx;
;             if (og + 1u == (tg + 1u) * nx) xb_add(&bar[XB_TOPGEN], 1u);
;             else XB_SPIN(xb_ld(&bar[XB_TOPGEN]) == tg, bar);
;             __builtin_amdgcn_fence(__ATOMIC_ACQUIRE, "agent");
;             xb_add(&bar[XB_XGEN(b.x)], 1u);
;             asm volatile("s_waitcnt vmcnt(0)" ::: "memory");
;         } else {
;             XB_SPIN(xb_ld(&bar[XB_XGEN(b.x)]) == gen, bar);
.LBB0_172:
	s_mov_b64 s[16:17], exec
	v_mbcnt_lo_u32_b32 v1, s16, 0
	v_mbcnt_hi_u32_b32 v1, s17, v1
	v_cmp_eq_u32_e32 vcc, 0, v1
	s_and_saveexec_b64 s[10:11], vcc
	s_cbranch_execz .LBB0_174
	s_bcnt1_i32_b64 s2, s[16:17]
	v_readlane_b32 s14, v252, 39
	v_mov_b32_e32 v3, s2
	v_readlane_b32 s15, v252, 40
	s_nop 4
	global_atomic_add v3, v217, v3, s[14:15] sc0
	buffer_inv sc1
.LBB0_174:
	s_or_b64 exec, exec, s[10:11]
	v_cvt_f32_u32_e32 v4, v2
	s_waitcnt vmcnt(1)
	v_readfirstlane_b32 s2, v3
	v_sub_u32_e32 v3, 0, v2
	v_rcp_iflag_f32_e32 v4, v4
	v_add_u32_e32 v5, s2, v1
	v_mul_f32_e32 v4, 0x4f7ffffe, v4
	v_cvt_u32_f32_e32 v4, v4
	v_mul_lo_u32 v1, v3, v4
	v_mul_hi_u32 v1, v4, v1
	v_add_u32_e32 v1, v4, v1
	v_mul_hi_u32 v1, v5, v1
	v_mul_lo_u32 v3, v1, v2
	v_sub_u32_e32 v3, v5, v3
	v_add_u32_e32 v4, 1, v1
	v_cmp_ge_u32_e32 vcc, v3, v2
	s_nop 1
	v_cndmask_b32_e32 v1, v1, v4, vcc
	v_sub_u32_e32 v4, v3, v2
	v_cndmask_b32_e32 v3, v3, v4, vcc
	v_add_u32_e32 v4, 1, v1
	v_cmp_ge_u32_e32 vcc, v3, v2
	v_add_u32_e32 v3, 1, v5
	s_nop 0
	v_cndmask_b32_e32 v1, v1, v4, vcc
	v_mul_lo_u32 v4, v2, v1
	v_add_u32_e32 v2, v4, v2
	v_cmp_ne_u32_e32 vcc, v3, v2
	s_and_saveexec_b64 s[10:11], vcc
	s_xor_b64 s[10:11], exec, s[10:11]
	s_cbranch_execz .LBB0_188
	s_waitcnt lgkmcnt(0)
	global_load_dword v0, v217, s[48:49] sc1
	s_waitcnt vmcnt(0)
	v_cmp_eq_u32_e32 vcc, v0, v1
	s_and_saveexec_b64 s[16:17], vcc
	s_cbranch_execz .LBB0_187
	s_mov_b32 s2, 1
	s_mov_b64 s[20:21], 0
	s_branch .LBB0_178

; __device__ __forceinline__ unsigned xb_ld(unsigned* p)              { return __hip_atomic_load(p, __ATOMIC_RELAXED, __HIP_MEMORY_SCOPE_AGENT); }
; #define XB_SPIN(cond, bar) do { unsigned _sp = 0; while (cond) { __builtin_amdgcn_s_sleep(1); \
;     if ((++_sp & 255u) == 0u) { if (xb_ld(&(bar)[XB_TMO])) break; if (_sp > XB_SPIN_CAP) { atomicAdd(&(bar)[XB_TMO], 1u); break; } } } } while (0)
; __device__ __forceinline__ void xcd_barrier(const XcdBarrier& b) {
;     ...
;             XB_SPIN(xb_ld(&bar[XB_XGEN(b.x)]) == gen, bar);
;             __builtin_amdgcn_fence(__ATOMIC_ACQUIRE, "agent");
;             asm volatile("s_waitcnt vmcnt(0)" ::: "memory");
.LBB0_187:
	s_or_b64 exec, exec, s[16:17]
	s_waitcnt vmcnt(0)
	s_waitcnt vmcnt(0)

; __device__ __forceinline__ unsigned xb_add(unsigned* p, unsigned v) { return __hip_atomic_fetch_add(p, v, __ATOMIC_RELAXED, __HIP_MEMORY_SCOPE_AGENT); }
; __device__ __forceinline__ void xcd_barrier(const XcdBarrier& b) {
;     ...
;             __builtin_amdgcn_fence(__ATOMIC_ACQUIRE, "agent");
;             xb_add(&bar[XB_XGEN(b.x)], 1u);
.LBB0_205:
	s_or_b64 exec, exec, s[10:11]
	s_mov_b64 s[10:11], exec
	v_mbcnt_lo_u32_b32 v0, s10, 0
	v_mbcnt_hi_u32_b32 v0, s11, v0
	v_cmp_eq_u32_e32 vcc, 0, v0
	s_waitcnt vmcnt(0)
	s_and_saveexec_b64 s[16:17], vcc
	s_cbranch_execz .LBB0_207
	s_bcnt1_i32_b64 s2, s[10:11]
	v_mov_b32_e32 v0, s2
	global_atomic_add v217, v0, s[48:49]

; __device__ __forceinline__ unsigned xb_ld(unsigned* p)              { return __hip_atomic_load(p, __ATOMIC_RELAXED, __HIP_MEMORY_SCOPE_AGENT); }
; __device__ __forceinline__ unsigned xb_add(unsigned* p, unsigned v) { return __hip_atomic_fetch_add(p, v, __ATOMIC_RELAXED, __HIP_MEMORY_SCOPE_AGENT); }
; #define XB_SPIN(cond, bar) do { unsigned _sp = 0; while (cond) { __builtin_amdgcn_s_sleep(1); \
;     if ((++_sp & 255u) == 0u) { if (xb_ld(&(bar)[XB_TMO])) break; if (_sp > XB_SPIN_CAP) { atomicAdd(&(bar)[XB_TMO], 1u); break; } } } } while (0)
; __device__ __forceinline__ void xcd_barrier(const XcdBarrier& b) {
;     ...
;         const unsigned old = xb_add(&bar[XB_XSUB(b.x)], 1u);
;         const unsigned gen = old / nloc;
;         if (old + 1u == (gen + 1u) * nloc) {
;             __builtin_amdgcn_fence(__ATOMIC_RELEASE, "agent");
;             asm volatile("s_waitcnt vmcnt(0)" ::: "memory");
;             const unsigned og = xb_add(&bar[XB_TOP], 1u);
;             const unsigned tg = og / nx;
;             if (og + 1u == (tg + 1u) * nx) xb_add(&bar[XB_TOPGEN], 1u);
;             else XB_SPIN(xb_ld(&bar[XB_TOPGEN]) == tg, bar);
;             __builtin_amdgcn_fence(__ATOMIC_ACQUIRE, "agent");
;             xb_add(&bar[XB_XGEN(b.x)], 1u);
;             asm volatile("s_waitcnt vmcnt(0)" ::: "memory");
;         } else {
;             XB_SPIN(xb_ld(&bar[XB_XGEN(b.x)]) == gen, bar);
.LBB0_233:
	s_mov_b64 s[8:9], exec
	v_mbcnt_lo_u32_b32 v1, s8, 0
	v_mbcnt_hi_u32_b32 v1, s9, v1
	v_cmp_eq_u32_e32 vcc, 0, v1
	s_and_saveexec_b64 s[4:5], vcc
	s_cbranch_execz .LBB0_235
	s_bcnt1_i32_b64 s2, s[8:9]
	v_readlane_b32 s8, v252, 39
	v_mov_b32_e32 v3, s2
	v_readlane_b32 s9, v252, 40
	s_nop 4
	global_atomic_add v3, v217, v3, s[8:9] sc0
	buffer_inv sc1
.LBB0_235:
	s_or_b64 exec, exec, s[4:5]
	v_cvt_f32_u32_e32 v4, v2
	s_waitcnt vmcnt(1)
	v_readfirstlane_b32 s2, v3
	v_sub_u32_e32 v3, 0, v2
	v_rcp_iflag_f32_e32 v4, v4
	v_add_u32_e32 v5, s2, v1
	v_mul_f32_e32 v4, 0x4f7ffffe, v4
	v_cvt_u32_f32_e32 v4, v4
	v_mul_lo_u32 v1, v3, v4
	v_mul_hi_u32 v1, v4, v1
	v_add_u32_e32 v1, v4, v1
	v_mul_hi_u32 v1, v5, v1
	v_mul_lo_u32 v3, v1, v2
	v_sub_u32_e32 v3, v5, v3
	v_add_u32_e32 v4, 1, v1
	v_cmp_ge_u32_e32 vcc, v3, v2
	s_nop 1
	v_cndmask_b32_e32 v1, v1, v4, vcc
	v_sub_u32_e32 v4, v3, v2
	v_cndmask_b32_e32 v3, v3, v4, vcc
	v_add_u32_e32 v4, 1, v1
	v_cmp_ge_u32_e32 vcc, v3, v2
	v_add_u32_e32 v3, 1, v5
	s_nop 0
	v_cndmask_b32_e32 v1, v1, v4, vcc
	v_mul_lo_u32 v4, v2, v1
	v_add_u32_e32 v2, v4, v2
	v_cmp_ne_u32_e32 vcc, v3, v2
	s_and_saveexec_b64 s[4:5], vcc
	s_xor_b64 s[4:5], exec, s[4:5]
	s_cbranch_execz .LBB0_249
	s_waitcnt lgkmcnt(0)
	global_load_dword v0, v217, s[48:49] sc1
	s_waitcnt vmcnt(0)
	v_cmp_eq_u32_e32 vcc, v0, v1
	s_and_saveexec_b64 s[8:9], vcc
	s_cbranch_execz .LBB0_248
	s_mov_b32 s2, 1
	s_mov_b64 s[10:11], 0
	s_branch .LBB0_239

; __device__ __forceinline__ unsigned xb_ld(unsigned* p)              { return __hip_atomic_load(p, __ATOMIC_RELAXED, __HIP_MEMORY_SCOPE_AGENT); }
; #define XB_SPIN(cond, bar) do { unsigned _sp = 0; while (cond) { __builtin_amdgcn_s_sleep(1); \
;     if ((++_sp & 255u) == 0u) { if (xb_ld(&(bar)[XB_TMO])) break; if (_sp > XB_SPIN_CAP) { atomicAdd(&(bar)[XB_TMO], 1u); break; } } } } while (0)
; __device__ __forceinline__ void xcd_barrier(const XcdBarrier& b) {
;     ...
;             XB_SPIN(xb_ld(&bar[XB_XGEN(b.x)]) == gen, bar);
;             __builtin_amdgcn_fence(__ATOMIC_ACQUIRE, "agent");
;             asm volatile("s_waitcnt vmcnt(0)" ::: "memory");
.LBB0_248:
	s_or_b64 exec, exec, s[8:9]
	s_waitcnt vmcnt(0)
	s_waitcnt vmcnt(0)

; __device__ __forceinline__ unsigned xb_add(unsigned* p, unsigned v) { return __hip_atomic_fetch_add(p, v, __ATOMIC_RELAXED, __HIP_MEMORY_SCOPE_AGENT); }
; __device__ __forceinline__ void xcd_barrier(const XcdBarrier& b) {
;     ...
;             __builtin_amdgcn_fence(__ATOMIC_ACQUIRE, "agent");
;             xb_add(&bar[XB_XGEN(b.x)], 1u);
.LBB0_266:
	s_or_b64 exec, exec, s[4:5]
	s_mov_b64 s[4:5], exec
	v_mbcnt_lo_u32_b32 v0, s4, 0
	v_mbcnt_hi_u32_b32 v0, s5, v0
	v_cmp_eq_u32_e32 vcc, 0, v0
	s_waitcnt vmcnt(0)
	s_and_saveexec_b64 s[8:9], vcc
	s_cbranch_execz .LBB0_268
	s_bcnt1_i32_b64 s2, s[4:5]
	v_mov_b32_e32 v0, s2
	global_atomic_add v217, v0, s[48:49]

; __device__ __forceinline__ float xpart16(float v, bool oddrow) { auto r = __builtin_amdgcn_permlane16_swap(__float_as_uint(v), __float_as_uint(v), false, false); return __uint_as_float(oddrow ? r[0] : r[1]); }
; __device__ __forceinline__ unsigned cvt_pk_bf16(float lo, float hi) { unsigned r; asm volatile("v_cvt_pk_bf16_f32 %0, %1, %2" : "=v"(r) : "v"(lo), "v"(hi)); return r; }
;     __device__ __forceinline__ void operator()(f32x4 (&acc)[2][2][4][2], const Unit& u, int wr, int wc, int lane) const {
;     ...
;             for (int m = 0; m < 4; ++m) {
;                 const unsigned lo = ((unsigned)(m * 16 + fr) * 3072u + 8u * fq) * 2u;
;                 const int s = (rowu + m * 16 + fr) & (SEQ - 1);
; #pragma unroll
;                 for (int bj = 0; bj < 2; ++bj) {
;                     f32x4 v0 = acc[ai][bj][m][0], v1 = acc[ai][bj][m][1];
;                     if (ropesel) {
;                         f32x4 p0, p1;
; #pragma unroll
;                         for (int j = 0; j < 4; ++j) { p0[j] = xpart16(v0[j], (fq & 1) != 0); p1[j] = xpart16(v1[j], (fq & 1) != 0); }
;                         if (rope) {
;                             const f32x4 ca = gld<f32x4>(rc, (unsigned)s * 32u), cb = gld<f32x4>(rc + 4, (unsigned)s * 32u), sa = gld<f32x4>(rs, (unsigned)s * 32u), sb = gld<f32x4>(rs + 4, (unsigned)s * 32u);
;                             if (fq == 0) { v0 = v0 * ca - p0 * sa; v1 = v1 * cb - p1 * sb; }
;                             else { v0 = v0 * ca + p0 * sa; v1 = v1 * cb + p1 * sb; }
;                         }
;                     }
;                     v0 = v0 * osc; v1 = v1 * osc;
;                     u32x4 w; w.x = cvt_pk_bf16(v0[0], v0[1]); w.y = cvt_pk_bf16(v0[2], v0[3]); w.z = cvt_pk_bf16(v1[0], v1[1]); w.w = cvt_pk_bf16(v1[2], v1[3]);
;                     gst<u32x4>(ou + bj * HALF, lo, w);
.LBB0_287:
	s_cmp_lt_i32 s39, 8
	s_cselect_b64 s[10:11], -1, 0
	s_lshl_b32 s23, s46, 8
	s_and_b64 s[10:11], s[20:21], s[10:11]
	s_add_i32 s23, s23, s33
	v_mbcnt_lo_u32_b32 v151, -1, 0
	v_mbcnt_hi_u32_b32 v151, -1, v151
	v_cndmask_b32_e64 v132, 0, 1, s[10:11]
	v_and_b32_e32 v150, 15, v151
	v_and_b32_e32 v133, 16, v151
	s_and_b32 s46, s23, 0xfc0
	v_cmp_gt_i32_e32 vcc, 32, v151
	v_cmp_eq_u32_e64 s[44:45], 0, v133
	v_or_b32_e32 v133, s46, v150
	v_cmp_ne_u32_e64 s[46:47], 1, v132
	s_and_b64 s[10:11], s[10:11], vcc
	v_cmp_lt_u32_e64 s[42:43], 15, v151
	s_and_b64 vcc, exec, s[46:47]
	v_lshlrev_b32_e32 v216, 5, v133
	s_cbranch_vccnz .LBB0_295
	v_mov_b32_e32 v132, v124
	v_mov_b32_e32 v133, v124
	v_mov_b32_e32 v136, v120
	v_mov_b32_e32 v137, v120
	v_mov_b32_e32 v134, v125
	v_mov_b32_e32 v135, v125
	v_mov_b32_e32 v140, v121
	v_mov_b32_e32 v141, v121
	v_mov_b32_e32 v138, v126
	v_mov_b32_e32 v139, v126
	v_mov_b32_e32 v144, v122
	v_mov_b32_e32 v145, v122
	v_mov_b32_e32 v142, v127
	v_mov_b32_e32 v143, v127
	v_mov_b32_e32 v146, v123
	v_mov_b32_e32 v147, v123
	v_permlane16_swap_b32_e32 v132, v133
	v_permlane16_swap_b32_e32 v136, v137
	v_permlane16_swap_b32_e32 v134, v135
	v_permlane16_swap_b32_e32 v140, v141
	v_permlane16_swap_b32_e32 v138, v139
	v_permlane16_swap_b32_e32 v144, v145
	v_permlane16_swap_b32_e32 v142, v143
	v_permlane16_swap_b32_e32 v146, v147
	s_and_saveexec_b64 s[58:59], s[10:11]
	s_cbranch_execz .LBB0_294
	v_cndmask_b32_e64 v162, v144, v145, s[44:45]
	v_cndmask_b32_e64 v144, v132, v133, s[44:45]
	v_lshl_add_u64 v[132:133], s[4:5], 0, v[216:217]
	v_cndmask_b32_e64 v160, v136, v137, s[44:45]
	v_cndmask_b32_e64 v145, v134, v135, s[44:45]
	v_lshl_add_u64 v[248:249], s[4:5], 0, v[216:217]
	v_lshl_add_u64 v[250:251], s[8:9], 0, v[216:217]
	s_mov_b64 vcc, 0x1000
	v_lshl_add_u64 v[218:219], v[248:249], 0, vcc
	v_lshl_add_u64 v[220:221], v[250:251], 0, vcc
	global_load_dwordx4 v[168:171], v[248:249], off offset:16
	global_load_dwordx4 v[164:167], v[248:249], off
	global_load_dwordx4 v[176:179], v[250:251], off offset:16
	global_load_dwordx4 v[172:175], v[250:251], off
	global_load_dwordx4 v[184:187], v[248:249], off offset:528
	global_load_dwordx4 v[180:183], v[248:249], off offset:512
	global_load_dwordx4 v[244:247], v[250:251], off offset:528
	global_load_dwordx4 v[188:191], v[250:251], off offset:512
	v_lshl_add_u64 v[132:133], s[8:9], 0, v[216:217]
	v_cndmask_b32_e64 v161, v140, v141, s[44:45]
	v_cndmask_b32_e64 v138, v138, v139, s[44:45]
	v_cndmask_b32_e64 v139, v142, v143, s[44:45]
	v_cndmask_b32_e64 v163, v146, v147, s[44:45]
	s_waitcnt vmcnt(4)
	v_mov_b32_e32 v152, v168
	v_mov_b32_e32 v153, v169
	v_mov_b32_e32 v154, v170
	v_mov_b32_e32 v155, v171
	v_mov_b32_e32 v134, v164
	v_mov_b32_e32 v135, v165
	v_mov_b32_e32 v136, v166
	v_mov_b32_e32 v137, v167
	v_mov_b32_e32 v156, v176
	v_mov_b32_e32 v157, v177
	v_mov_b32_e32 v158, v178
	v_mov_b32_e32 v159, v179
	v_mov_b32_e32 v140, v172
	v_mov_b32_e32 v141, v173
	v_mov_b32_e32 v142, v174
	v_mov_b32_e32 v143, v175
	v_pk_mul_f32 v[132:133], v[126:127], v[136:137]
	v_pk_mul_f32 v[134:135], v[124:125], v[134:135]
	v_pk_mul_f32 v[136:137], v[122:123], v[154:155]
	v_pk_mul_f32 v[146:147], v[158:159], v[162:163]
	v_pk_mul_f32 v[140:141], v[140:141], v[144:145]
	v_pk_mul_f32 v[144:145], v[142:143], v[138:139]
	v_pk_mul_f32 v[138:139], v[120:121], v[152:153]
	v_pk_mul_f32 v[142:143], v[156:157], v[160:161]
	s_and_saveexec_b64 s[60:61], s[42:43]
	s_xor_b64 s[60:61], exec, s[60:61]
	v_pk_add_f32 v[126:127], v[132:133], v[144:145]
	v_pk_add_f32 v[124:125], v[134:135], v[140:141]
	v_pk_add_f32 v[122:123], v[136:137], v[146:147]
	v_pk_add_f32 v[120:121], v[138:139], v[142:143]
	s_andn2_saveexec_b64 s[60:61], s[60:61]
	v_sub_f32_e32 v127, v133, v145
	v_sub_f32_e32 v126, v132, v144
	v_sub_f32_e32 v125, v135, v141
	v_sub_f32_e32 v124, v134, v140
	v_sub_f32_e32 v123, v137, v147
	v_sub_f32_e32 v122, v136, v146
	v_sub_f32_e32 v121, v139, v143
	v_sub_f32_e32 v120, v138, v142
	s_or_b64 exec, exec, s[60:61]

; __device__ __forceinline__ float xpart16(float v, bool oddrow) { auto r = __builtin_amdgcn_permlane16_swap(__float_as_uint(v), __float_as_uint(v), false, false); return __uint_as_float(oddrow ? r[0] : r[1]); }
; __device__ __forceinline__ unsigned cvt_pk_bf16(float lo, float hi) { unsigned r; asm volatile("v_cvt_pk_bf16_f32 %0, %1, %2" : "=v"(r) : "v"(lo), "v"(hi)); return r; }
;     __device__ __forceinline__ void operator()(f32x4 (&acc)[2][2][4][2], const Unit& u, int wr, int wc, int lane) const {
;     ...
;                 for (int bj = 0; bj < 2; ++bj) {
;                     f32x4 v0 = acc[ai][bj][m][0], v1 = acc[ai][bj][m][1];
;                     if (ropesel) {
;                         f32x4 p0, p1;
; #pragma unroll
;                         for (int j = 0; j < 4; ++j) { p0[j] = xpart16(v0[j], (fq & 1) != 0); p1[j] = xpart16(v1[j], (fq & 1) != 0); }
;                         if (rope) {
;                             const f32x4 ca = gld<f32x4>(rc, (unsigned)s * 32u), cb = gld<f32x4>(rc + 4, (unsigned)s * 32u), sa = gld<f32x4>(rs, (unsigned)s * 32u), sb = gld<f32x4>(rs + 4, (unsigned)s * 32u);
;                             if (fq == 0) { v0 = v0 * ca - p0 * sa; v1 = v1 * cb - p1 * sb; }
;                             else { v0 = v0 * ca + p0 * sa; v1 = v1 * cb + p1 * sb; }
;                         }
;                     }
;                     v0 = v0 * osc; v1 = v1 * osc;
;                     u32x4 w; w.x = cvt_pk_bf16(v0[0], v0[1]); w.y = cvt_pk_bf16(v0[2], v0[3]); w.z = cvt_pk_bf16(v1[0], v1[1]); w.w = cvt_pk_bf16(v1[2], v1[3]);
;                     gst<u32x4>(ou + bj * HALF, lo, w);
.LBB0_295:
	s_cmp_lt_i32 s39, 4
	s_cselect_b64 vcc, -1, 0
	s_lshl_b32 s58, s39, 8
	s_ashr_i32 s59, s58, 31
	s_mul_i32 s49, s23, 0x1800
	s_mul_hi_i32 s39, s23, 0x1800
	s_add_u32 s49, s30, s49
	s_addc_u32 s39, s31, s39
	s_lshl_b64 s[58:59], s[58:59], 1
	s_add_u32 s49, s49, s58
	s_addc_u32 s39, s39, s59
	s_add_u32 s60, s49, s37
	v_cndmask_b32_e32 v132, 1.0, v235, vcc
	v_and_b32_e32 v133, -16, v151
	s_addc_u32 s61, s39, 0
	s_movk_i32 s39, 0x1800
	v_mad_u32_u24 v134, v150, s39, v133
	v_pk_mul_f32 v[136:137], v[132:133], v[122:123] op_sel_hi:[0,1]
	v_pk_mul_f32 v[122:123], v[132:133], v[120:121] op_sel_hi:[0,1]
	s_and_b64 vcc, exec, s[46:47]
	v_pk_mul_f32 v[126:127], v[132:133], v[126:127] op_sel_hi:[0,1]
	v_pk_mul_f32 v[124:125], v[132:133], v[124:125] op_sel_hi:[0,1]
	v_cvt_pk_bf16_f32 v120, v124, v125
	v_cvt_pk_bf16_f32 v121, v126, v127
	v_cvt_pk_bf16_f32 v122, v122, v123
	v_cvt_pk_bf16_f32 v123, v136, v137
	global_store_dwordx4 v134, v[120:123], s[60:61]
	s_cbranch_vccnz .LBB0_303
	s_nop 0
	v_mov_b32_e32 v120, v116
	v_mov_b32_e32 v121, v116
	v_mov_b32_e32 v124, v112
	v_mov_b32_e32 v125, v112
	v_mov_b32_e32 v122, v117
	v_mov_b32_e32 v123, v117
	v_mov_b32_e32 v133, v113
	v_mov_b32_e32 v135, v113
	v_mov_b32_e32 v126, v118
	v_mov_b32_e32 v127, v118
	v_mov_b32_e32 v138, v114
	v_mov_b32_e32 v139, v114
	v_mov_b32_e32 v136, v119
	v_mov_b32_e32 v137, v119
	v_mov_b32_e32 v140, v115
	v_mov_b32_e32 v141, v115
	v_permlane16_swap_b32_e32 v120, v121
	v_permlane16_swap_b32_e32 v124, v125
	v_permlane16_swap_b32_e32 v122, v123
	v_permlane16_swap_b32_e32 v133, v135
	v_permlane16_swap_b32_e32 v126, v127
	v_permlane16_swap_b32_e32 v138, v139
	v_permlane16_swap_b32_e32 v136, v137
	v_permlane16_swap_b32_e32 v140, v141
	s_and_saveexec_b64 s[62:63], s[10:11]
	s_cbranch_execz .LBB0_302
	v_cndmask_b32_e64 v157, v140, v141, s[44:45]
	v_cndmask_b32_e64 v140, v120, v121, s[44:45]
	v_lshl_add_u64 v[120:121], s[4:5], 0, v[216:217]
	v_cndmask_b32_e64 v146, v124, v125, s[44:45]
	v_cndmask_b32_e64 v141, v122, v123, s[44:45]
	v_lshl_add_u64 v[120:121], s[8:9], 0, v[216:217]
	v_cndmask_b32_e64 v156, v138, v139, s[44:45]
	v_cndmask_b32_e64 v126, v126, v127, s[44:45]
	v_cndmask_b32_e64 v127, v136, v137, s[44:45]
	v_cndmask_b32_e64 v147, v133, v135, s[44:45]
	v_mov_b32_e32 v142, v168
	v_mov_b32_e32 v143, v169
	v_mov_b32_e32 v144, v170
	v_mov_b32_e32 v145, v171
	v_mov_b32_e32 v122, v164
	v_mov_b32_e32 v123, v165
	v_mov_b32_e32 v124, v166
	v_mov_b32_e32 v125, v167
	v_mov_b32_e32 v152, v176
	v_mov_b32_e32 v153, v177
	v_mov_b32_e32 v154, v178
	v_mov_b32_e32 v155, v179
	v_mov_b32_e32 v136, v172
	v_mov_b32_e32 v137, v173
	v_mov_b32_e32 v138, v174
	v_mov_b32_e32 v139, v175
	v_pk_mul_f32 v[120:121], v[118:119], v[124:125]
	v_pk_mul_f32 v[122:123], v[116:117], v[122:123]
	v_pk_mul_f32 v[124:125], v[114:115], v[144:145]
	v_pk_mul_f32 v[136:137], v[136:137], v[140:141]
	v_pk_mul_f32 v[140:141], v[138:139], v[126:127]
	v_pk_mul_f32 v[126:127], v[112:113], v[142:143]
	v_pk_mul_f32 v[138:139], v[152:153], v[146:147]
	v_pk_mul_f32 v[142:143], v[154:155], v[156:157]
	s_and_saveexec_b64 s[64:65], s[42:43]
	s_xor_b64 s[68:69], exec, s[64:65]
	v_pk_add_f32 v[118:119], v[120:121], v[140:141]
	v_pk_add_f32 v[116:117], v[122:123], v[136:137]
	v_pk_add_f32 v[114:115], v[124:125], v[142:143]
	v_pk_add_f32 v[112:113], v[126:127], v[138:139]
	s_andn2_saveexec_b64 s[68:69], s[68:69]
	v_sub_f32_e32 v119, v121, v141
	v_sub_f32_e32 v118, v120, v140
	v_sub_f32_e32 v117, v123, v137
	v_sub_f32_e32 v116, v122, v136
	v_sub_f32_e32 v115, v125, v143
	v_sub_f32_e32 v114, v124, v142
	v_sub_f32_e32 v113, v127, v139
	v_sub_f32_e32 v112, v126, v138
	s_or_b64 exec, exec, s[68:69]
	s_mov_b64 s[68:69], 0x2c00

; __device__ __forceinline__ float xpart16(float v, bool oddrow) { auto r = __builtin_amdgcn_permlane16_swap(__float_as_uint(v), __float_as_uint(v), false, false); return __uint_as_float(oddrow ? r[0] : r[1]); }
; __device__ __forceinline__ unsigned cvt_pk_bf16(float lo, float hi) { unsigned r; asm volatile("v_cvt_pk_bf16_f32 %0, %1, %2" : "=v"(r) : "v"(lo), "v"(hi)); return r; }
;     __device__ __forceinline__ void operator()(f32x4 (&acc)[2][2][4][2], const Unit& u, int wr, int wc, int lane) const {
;     ...
;                 for (int bj = 0; bj < 2; ++bj) {
;                     f32x4 v0 = acc[ai][bj][m][0], v1 = acc[ai][bj][m][1];
;                     if (ropesel) {
;                         f32x4 p0, p1;
; #pragma unroll
;                         for (int j = 0; j < 4; ++j) { p0[j] = xpart16(v0[j], (fq & 1) != 0); p1[j] = xpart16(v1[j], (fq & 1) != 0); }
;                         if (rope) {
;                             const f32x4 ca = gld<f32x4>(rc, (unsigned)s * 32u), cb = gld<f32x4>(rc + 4, (unsigned)s * 32u), sa = gld<f32x4>(rs, (unsigned)s * 32u), sb = gld<f32x4>(rs + 4, (unsigned)s * 32u);
;                             if (fq == 0) { v0 = v0 * ca - p0 * sa; v1 = v1 * cb - p1 * sb; }
;                             else { v0 = v0 * ca + p0 * sa; v1 = v1 * cb + p1 * sb; }
;                         }
;                     }
;                     v0 = v0 * osc; v1 = v1 * osc;
;                     u32x4 w; w.x = cvt_pk_bf16(v0[0], v0[1]); w.y = cvt_pk_bf16(v0[2], v0[3]); w.z = cvt_pk_bf16(v1[0], v1[1]); w.w = cvt_pk_bf16(v1[2], v1[3]);
;                     gst<u32x4>(ou + bj * HALF, lo, w);
.LBB0_303:
	v_mov_b32_e32 v133, v132
	v_mov_b32_e32 v135, v217
	v_mov_b32_e32 v120, v132
	v_mov_b32_e32 v121, v132
	v_lshl_add_u64 v[122:123], s[60:61], 0, v[134:135]
	v_pk_mul_f32 v[124:125], v[120:121], v[114:115]
	v_pk_mul_f32 v[114:115], v[132:133], v[112:113]
	s_and_b64 vcc, exec, s[46:47]
	v_pk_mul_f32 v[118:119], v[120:121], v[118:119]
	v_pk_mul_f32 v[116:117], v[132:133], v[116:117]
	s_nop 0
	v_cvt_pk_bf16_f32 v112, v116, v117
	v_cvt_pk_bf16_f32 v113, v118, v119
	v_cvt_pk_bf16_f32 v114, v114, v115
	v_cvt_pk_bf16_f32 v115, v124, v125
	global_store_dwordx4 v[122:123], v[112:115], off offset:256
	s_cbranch_vccnz .LBB0_311
	s_nop 0
	v_mov_b32_e32 v112, v108
	v_mov_b32_e32 v113, v108
	v_mov_b32_e32 v116, v104
	v_mov_b32_e32 v117, v104
	v_mov_b32_e32 v114, v109
	v_mov_b32_e32 v115, v109
	v_mov_b32_e32 v122, v105
	v_mov_b32_e32 v123, v105
	v_mov_b32_e32 v118, v110
	v_mov_b32_e32 v119, v110
	v_mov_b32_e32 v126, v106
	v_mov_b32_e32 v127, v106
	v_mov_b32_e32 v124, v111
	v_mov_b32_e32 v125, v111
	v_mov_b32_e32 v136, v107
	v_mov_b32_e32 v137, v107
	v_permlane16_swap_b32_e32 v112, v113
	v_permlane16_swap_b32_e32 v116, v117
	v_permlane16_swap_b32_e32 v114, v115
	v_permlane16_swap_b32_e32 v122, v123
	v_permlane16_swap_b32_e32 v118, v119
	v_permlane16_swap_b32_e32 v126, v127
	v_permlane16_swap_b32_e32 v124, v125
	v_permlane16_swap_b32_e32 v136, v137
	s_and_saveexec_b64 s[62:63], s[10:11]
	s_cbranch_execz .LBB0_310
	v_cndmask_b32_e64 v146, v126, v127, s[44:45]
	v_cndmask_b32_e64 v126, v112, v113, s[44:45]
	v_lshl_add_u64 v[112:113], s[4:5], 0, v[216:217]
	v_cndmask_b32_e64 v144, v116, v117, s[44:45]
	v_cndmask_b32_e64 v147, v136, v137, s[44:45]
	v_cndmask_b32_e64 v127, v114, v115, s[44:45]
	global_load_dwordx4 v[168:171], v[248:249], off offset:1040
	global_load_dwordx4 v[164:167], v[248:249], off offset:1024
	global_load_dwordx4 v[176:179], v[250:251], off offset:1040
	global_load_dwordx4 v[172:175], v[250:251], off offset:1024
	v_lshl_add_u64 v[112:113], s[8:9], 0, v[216:217]
	v_cndmask_b32_e64 v145, v122, v123, s[44:45]
	v_cndmask_b32_e64 v118, v118, v119, s[44:45]
	v_cndmask_b32_e64 v119, v124, v125, s[44:45]
	s_waitcnt vmcnt(6)
	v_mov_b32_e32 v136, v184
	v_mov_b32_e32 v137, v185
	v_mov_b32_e32 v138, v186
	v_mov_b32_e32 v139, v187
	v_mov_b32_e32 v114, v180
	v_mov_b32_e32 v115, v181
	v_mov_b32_e32 v116, v182
	v_mov_b32_e32 v117, v183
	v_mov_b32_e32 v140, v244
	v_mov_b32_e32 v141, v245
	v_mov_b32_e32 v142, v246
	v_mov_b32_e32 v143, v247
	v_mov_b32_e32 v122, v188
	v_mov_b32_e32 v123, v189
	v_mov_b32_e32 v124, v190
	v_mov_b32_e32 v125, v191
	v_pk_mul_f32 v[112:113], v[110:111], v[116:117]
	v_pk_mul_f32 v[114:115], v[108:109], v[114:115]
	v_pk_mul_f32 v[116:117], v[106:107], v[138:139]
	v_pk_mul_f32 v[122:123], v[122:123], v[126:127]
	v_pk_mul_f32 v[126:127], v[124:125], v[118:119]
	v_pk_mul_f32 v[118:119], v[104:105], v[136:137]
	v_pk_mul_f32 v[124:125], v[140:141], v[144:145]
	v_pk_mul_f32 v[136:137], v[142:143], v[146:147]
	s_and_saveexec_b64 s[64:65], s[42:43]
	s_xor_b64 s[68:69], exec, s[64:65]
	v_pk_add_f32 v[110:111], v[112:113], v[126:127]
	v_pk_add_f32 v[108:109], v[114:115], v[122:123]
	v_pk_add_f32 v[106:107], v[116:117], v[136:137]
	v_pk_add_f32 v[104:105], v[118:119], v[124:125]
	s_andn2_saveexec_b64 s[68:69], s[68:69]
	v_sub_f32_e32 v111, v113, v127
	v_sub_f32_e32 v110, v112, v126
	v_sub_f32_e32 v109, v115, v123
	v_sub_f32_e32 v108, v114, v122
	v_sub_f32_e32 v107, v117, v137
	v_sub_f32_e32 v106, v116, v136
	v_sub_f32_e32 v105, v119, v125
	v_sub_f32_e32 v104, v118, v124
	s_or_b64 exec, exec, s[68:69]
	s_mov_b64 s[68:69], 0x2c00

; __device__ __forceinline__ float xpart16(float v, bool oddrow) { auto r = __builtin_amdgcn_permlane16_swap(__float_as_uint(v), __float_as_uint(v), false, false); return __uint_as_float(oddrow ? r[0] : r[1]); }
; __device__ __forceinline__ unsigned cvt_pk_bf16(float lo, float hi) { unsigned r; asm volatile("v_cvt_pk_bf16_f32 %0, %1, %2" : "=v"(r) : "v"(lo), "v"(hi)); return r; }
;     __device__ __forceinline__ void operator()(f32x4 (&acc)[2][2][4][2], const Unit& u, int wr, int wc, int lane) const {
;     ...
;                 for (int bj = 0; bj < 2; ++bj) {
;                     f32x4 v0 = acc[ai][bj][m][0], v1 = acc[ai][bj][m][1];
;                     if (ropesel) {
;                         f32x4 p0, p1;
; #pragma unroll
;                         for (int j = 0; j < 4; ++j) { p0[j] = xpart16(v0[j], (fq & 1) != 0); p1[j] = xpart16(v1[j], (fq & 1) != 0); }
;                         if (rope) {
;                             const f32x4 ca = gld<f32x4>(rc, (unsigned)s * 32u), cb = gld<f32x4>(rc + 4, (unsigned)s * 32u), sa = gld<f32x4>(rs, (unsigned)s * 32u), sb = gld<f32x4>(rs + 4, (unsigned)s * 32u);
;                             if (fq == 0) { v0 = v0 * ca - p0 * sa; v1 = v1 * cb - p1 * sb; }
;                             else { v0 = v0 * ca + p0 * sa; v1 = v1 * cb + p1 * sb; }
;                         }
;                     }
;                     v0 = v0 * osc; v1 = v1 * osc;
;                     u32x4 w; w.x = cvt_pk_bf16(v0[0], v0[1]); w.y = cvt_pk_bf16(v0[2], v0[3]); w.z = cvt_pk_bf16(v1[0], v1[1]); w.w = cvt_pk_bf16(v1[2], v1[3]);
;                     gst<u32x4>(ou + bj * HALF, lo, w);
.LBB0_311:
	s_nop 0
	v_add_u32_e32 v112, 0x18000, v134
	v_pk_mul_f32 v[114:115], v[120:121], v[106:107]
	v_pk_mul_f32 v[106:107], v[132:133], v[104:105]
	s_and_b64 vcc, exec, s[46:47]
	v_pk_mul_f32 v[110:111], v[120:121], v[110:111]
	v_pk_mul_f32 v[108:109], v[132:133], v[108:109]
	s_nop 0
	v_cvt_pk_bf16_f32 v104, v108, v109
	v_cvt_pk_bf16_f32 v105, v110, v111
	v_cvt_pk_bf16_f32 v106, v106, v107
	v_cvt_pk_bf16_f32 v107, v114, v115
	global_store_dwordx4 v112, v[104:107], s[60:61]
	s_cbranch_vccnz .LBB0_319
	s_nop 0
	v_mov_b32_e32 v104, v100
	v_mov_b32_e32 v105, v100
	v_mov_b32_e32 v108, v96
	v_mov_b32_e32 v109, v96
	v_mov_b32_e32 v106, v101
	v_mov_b32_e32 v107, v101
	v_mov_b32_e32 v113, v97
	v_mov_b32_e32 v114, v97
	v_mov_b32_e32 v110, v102
	v_mov_b32_e32 v111, v102
	v_mov_b32_e32 v117, v98
	v_mov_b32_e32 v118, v98
	v_mov_b32_e32 v115, v103
	v_mov_b32_e32 v116, v103
	v_mov_b32_e32 v119, v99
	v_mov_b32_e32 v120, v99
	v_permlane16_swap_b32_e32 v104, v105
	v_permlane16_swap_b32_e32 v108, v109
	v_permlane16_swap_b32_e32 v106, v107
	v_permlane16_swap_b32_e32 v113, v114
	v_permlane16_swap_b32_e32 v110, v111
	v_permlane16_swap_b32_e32 v117, v118
	v_permlane16_swap_b32_e32 v115, v116
	v_permlane16_swap_b32_e32 v119, v120
	s_and_saveexec_b64 s[62:63], s[10:11]
	s_cbranch_execz .LBB0_318
	v_cndmask_b32_e64 v138, v117, v118, s[44:45]
	v_cndmask_b32_e64 v118, v104, v105, s[44:45]
	v_lshl_add_u64 v[104:105], s[4:5], 0, v[216:217]
	v_cndmask_b32_e64 v136, v108, v109, s[44:45]
	v_cndmask_b32_e64 v139, v119, v120, s[44:45]
	v_cndmask_b32_e64 v119, v106, v107, s[44:45]
	v_lshl_add_u64 v[104:105], s[8:9], 0, v[216:217]
	v_cndmask_b32_e64 v137, v113, v114, s[44:45]
	v_cndmask_b32_e64 v110, v110, v111, s[44:45]
	v_cndmask_b32_e64 v111, v115, v116, s[44:45]
	v_mov_b32_e32 v120, v184
	v_mov_b32_e32 v121, v185
	v_mov_b32_e32 v122, v186
	v_mov_b32_e32 v123, v187
	v_mov_b32_e32 v106, v180
	v_mov_b32_e32 v107, v181
	v_mov_b32_e32 v108, v182
	v_mov_b32_e32 v109, v183
	v_mov_b32_e32 v124, v244
	v_mov_b32_e32 v125, v245
	v_mov_b32_e32 v126, v246
	v_mov_b32_e32 v127, v247
	v_mov_b32_e32 v114, v188
	v_mov_b32_e32 v115, v189
	v_mov_b32_e32 v116, v190
	v_mov_b32_e32 v117, v191
	v_pk_mul_f32 v[104:105], v[102:103], v[108:109]
	v_pk_mul_f32 v[106:107], v[100:101], v[106:107]
	v_pk_mul_f32 v[108:109], v[98:99], v[122:123]
	v_pk_mul_f32 v[114:115], v[114:115], v[118:119]
	v_pk_mul_f32 v[118:119], v[116:117], v[110:111]
	v_pk_mul_f32 v[110:111], v[96:97], v[120:121]
	v_pk_mul_f32 v[116:117], v[124:125], v[136:137]
	v_pk_mul_f32 v[120:121], v[126:127], v[138:139]
	s_and_saveexec_b64 s[64:65], s[42:43]
	s_xor_b64 s[68:69], exec, s[64:65]
	v_pk_add_f32 v[102:103], v[104:105], v[118:119]
	v_pk_add_f32 v[100:101], v[106:107], v[114:115]
	v_pk_add_f32 v[98:99], v[108:109], v[120:121]
	v_pk_add_f32 v[96:97], v[110:111], v[116:117]
	s_andn2_saveexec_b64 s[68:69], s[68:69]
	v_sub_f32_e32 v103, v105, v119
	v_sub_f32_e32 v102, v104, v118
	v_sub_f32_e32 v101, v107, v115
	v_sub_f32_e32 v100, v106, v114
	v_sub_f32_e32 v99, v109, v121
	v_sub_f32_e32 v98, v108, v120
	v_sub_f32_e32 v97, v111, v117
	v_sub_f32_e32 v96, v110, v116
	s_or_b64 exec, exec, s[68:69]
	s_mov_b64 s[68:69], 0x2c00

; __device__ __forceinline__ float xpart16(float v, bool oddrow) { auto r = __builtin_amdgcn_permlane16_swap(__float_as_uint(v), __float_as_uint(v), false, false); return __uint_as_float(oddrow ? r[0] : r[1]); }
; __device__ __forceinline__ unsigned cvt_pk_bf16(float lo, float hi) { unsigned r; asm volatile("v_cvt_pk_bf16_f32 %0, %1, %2" : "=v"(r) : "v"(lo), "v"(hi)); return r; }
;     __device__ __forceinline__ void operator()(f32x4 (&acc)[2][2][4][2], const Unit& u, int wr, int wc, int lane) const {
;     ...
;                 for (int bj = 0; bj < 2; ++bj) {
;                     f32x4 v0 = acc[ai][bj][m][0], v1 = acc[ai][bj][m][1];
;                     if (ropesel) {
;                         f32x4 p0, p1;
; #pragma unroll
;                         for (int j = 0; j < 4; ++j) { p0[j] = xpart16(v0[j], (fq & 1) != 0); p1[j] = xpart16(v1[j], (fq & 1) != 0); }
;                         if (rope) {
;                             const f32x4 ca = gld<f32x4>(rc, (unsigned)s * 32u), cb = gld<f32x4>(rc + 4, (unsigned)s * 32u), sa = gld<f32x4>(rs, (unsigned)s * 32u), sb = gld<f32x4>(rs + 4, (unsigned)s * 32u);
;                             if (fq == 0) { v0 = v0 * ca - p0 * sa; v1 = v1 * cb - p1 * sb; }
;                             else { v0 = v0 * ca + p0 * sa; v1 = v1 * cb + p1 * sb; }
;                         }
;                     }
;                     v0 = v0 * osc; v1 = v1 * osc;
;                     u32x4 w; w.x = cvt_pk_bf16(v0[0], v0[1]); w.y = cvt_pk_bf16(v0[2], v0[3]); w.z = cvt_pk_bf16(v1[0], v1[1]); w.w = cvt_pk_bf16(v1[2], v1[3]);
;                     gst<u32x4>(ou + bj * HALF, lo, w);
.LBB0_319:
	v_mov_b32_e32 v113, v217
	v_mov_b32_e32 v104, v132
	v_mov_b32_e32 v105, v132
	v_lshl_add_u64 v[106:107], s[60:61], 0, v[112:113]
	v_pk_mul_f32 v[108:109], v[104:105], v[98:99]
	v_pk_mul_f32 v[98:99], v[132:133], v[96:97]
	s_and_b64 vcc, exec, s[46:47]
	v_pk_mul_f32 v[102:103], v[104:105], v[102:103]
	v_pk_mul_f32 v[100:101], v[132:133], v[100:101]
	s_nop 0
	v_cvt_pk_bf16_f32 v96, v100, v101
	v_cvt_pk_bf16_f32 v97, v102, v103
	v_cvt_pk_bf16_f32 v98, v98, v99
	v_cvt_pk_bf16_f32 v99, v108, v109
	global_store_dwordx4 v[106:107], v[96:99], off offset:256
	s_cbranch_vccnz .LBB0_327
	s_nop 0
	v_mov_b32_e32 v96, v92
	v_mov_b32_e32 v97, v92
	v_mov_b32_e32 v100, v88
	v_mov_b32_e32 v101, v88
	v_mov_b32_e32 v98, v93
	v_mov_b32_e32 v99, v93
	v_mov_b32_e32 v106, v89
	v_mov_b32_e32 v107, v89
	v_mov_b32_e32 v102, v94
	v_mov_b32_e32 v103, v94
	v_mov_b32_e32 v110, v90
	v_mov_b32_e32 v111, v90
	v_mov_b32_e32 v108, v95
	v_mov_b32_e32 v109, v95
	v_mov_b32_e32 v114, v91
	v_mov_b32_e32 v115, v91
	v_permlane16_swap_b32_e32 v96, v97
	v_permlane16_swap_b32_e32 v100, v101
	v_permlane16_swap_b32_e32 v98, v99
	v_permlane16_swap_b32_e32 v106, v107
	v_permlane16_swap_b32_e32 v102, v103
	v_permlane16_swap_b32_e32 v110, v111
	v_permlane16_swap_b32_e32 v108, v109
	v_permlane16_swap_b32_e32 v114, v115
	s_and_saveexec_b64 s[62:63], s[10:11]
	s_cbranch_execz .LBB0_326
	v_cndmask_b32_e64 v124, v110, v111, s[44:45]
	v_cndmask_b32_e64 v110, v96, v97, s[44:45]
	v_lshl_add_u64 v[96:97], s[4:5], 0, v[216:217]
	v_cndmask_b32_e64 v122, v100, v101, s[44:45]
	v_cndmask_b32_e64 v125, v114, v115, s[44:45]
	v_cndmask_b32_e64 v111, v98, v99, s[44:45]
	global_load_dwordx4 v[184:187], v[248:249], off offset:1552
	global_load_dwordx4 v[180:183], v[248:249], off offset:1536
	global_load_dwordx4 v[244:247], v[250:251], off offset:1552
	global_load_dwordx4 v[188:191], v[250:251], off offset:1536
	v_lshl_add_u64 v[96:97], s[8:9], 0, v[216:217]
	v_cndmask_b32_e64 v123, v106, v107, s[44:45]
	v_cndmask_b32_e64 v102, v102, v103, s[44:45]
	v_cndmask_b32_e64 v103, v108, v109, s[44:45]
	s_waitcnt vmcnt(6)
	v_mov_b32_e32 v114, v168
	v_mov_b32_e32 v115, v169
	v_mov_b32_e32 v116, v170
	v_mov_b32_e32 v117, v171
	v_mov_b32_e32 v98, v164
	v_mov_b32_e32 v99, v165
	v_mov_b32_e32 v100, v166
	v_mov_b32_e32 v101, v167
	v_mov_b32_e32 v118, v176
	v_mov_b32_e32 v119, v177
	v_mov_b32_e32 v120, v178
	v_mov_b32_e32 v121, v179
	v_mov_b32_e32 v106, v172
	v_mov_b32_e32 v107, v173
	v_mov_b32_e32 v108, v174
	v_mov_b32_e32 v109, v175
	v_pk_mul_f32 v[96:97], v[94:95], v[100:101]
	v_pk_mul_f32 v[98:99], v[92:93], v[98:99]
	v_pk_mul_f32 v[100:101], v[90:91], v[116:117]
	v_pk_mul_f32 v[106:107], v[106:107], v[110:111]
	v_pk_mul_f32 v[110:111], v[108:109], v[102:103]
	v_pk_mul_f32 v[102:103], v[88:89], v[114:115]
	v_pk_mul_f32 v[108:109], v[118:119], v[122:123]
	v_pk_mul_f32 v[114:115], v[120:121], v[124:125]
	s_and_saveexec_b64 s[64:65], s[42:43]
	s_xor_b64 s[68:69], exec, s[64:65]
	v_pk_add_f32 v[94:95], v[96:97], v[110:111]
	v_pk_add_f32 v[92:93], v[98:99], v[106:107]
	v_pk_add_f32 v[90:91], v[100:101], v[114:115]
	v_pk_add_f32 v[88:89], v[102:103], v[108:109]
	s_andn2_saveexec_b64 s[68:69], s[68:69]
	v_sub_f32_e32 v95, v97, v111
	v_sub_f32_e32 v94, v96, v110
	v_sub_f32_e32 v93, v99, v107
	v_sub_f32_e32 v92, v98, v106
	v_sub_f32_e32 v91, v101, v115
	v_sub_f32_e32 v90, v100, v114
	v_sub_f32_e32 v89, v103, v109
	v_sub_f32_e32 v88, v102, v108
	s_or_b64 exec, exec, s[68:69]
	s_mov_b64 s[68:69], 0x2c00

; __device__ __forceinline__ float xpart16(float v, bool oddrow) { auto r = __builtin_amdgcn_permlane16_swap(__float_as_uint(v), __float_as_uint(v), false, false); return __uint_as_float(oddrow ? r[0] : r[1]); }
; __device__ __forceinline__ unsigned cvt_pk_bf16(float lo, float hi) { unsigned r; asm volatile("v_cvt_pk_bf16_f32 %0, %1, %2" : "=v"(r) : "v"(lo), "v"(hi)); return r; }
;     __device__ __forceinline__ void operator()(f32x4 (&acc)[2][2][4][2], const Unit& u, int wr, int wc, int lane) const {
;     ...
;                 for (int bj = 0; bj < 2; ++bj) {
;                     f32x4 v0 = acc[ai][bj][m][0], v1 = acc[ai][bj][m][1];
;                     if (ropesel) {
;                         f32x4 p0, p1;
; #pragma unroll
;                         for (int j = 0; j < 4; ++j) { p0[j] = xpart16(v0[j], (fq & 1) != 0); p1[j] = xpart16(v1[j], (fq & 1) != 0); }
;                         if (rope) {
;                             const f32x4 ca = gld<f32x4>(rc, (unsigned)s * 32u), cb = gld<f32x4>(rc + 4, (unsigned)s * 32u), sa = gld<f32x4>(rs, (unsigned)s * 32u), sb = gld<f32x4>(rs + 4, (unsigned)s * 32u);
;                             if (fq == 0) { v0 = v0 * ca - p0 * sa; v1 = v1 * cb - p1 * sb; }
;                             else { v0 = v0 * ca + p0 * sa; v1 = v1 * cb + p1 * sb; }
;                         }
;                     }
;                     v0 = v0 * osc; v1 = v1 * osc;
;                     u32x4 w; w.x = cvt_pk_bf16(v0[0], v0[1]); w.y = cvt_pk_bf16(v0[2], v0[3]); w.z = cvt_pk_bf16(v1[0], v1[1]); w.w = cvt_pk_bf16(v1[2], v1[3]);
;                     gst<u32x4>(ou + bj * HALF, lo, w);
.LBB0_327:
	s_nop 0
	v_add_u32_e32 v96, 0x30000, v134
	v_pk_mul_f32 v[98:99], v[104:105], v[90:91]
	v_pk_mul_f32 v[90:91], v[132:133], v[88:89]
	s_and_b64 vcc, exec, s[46:47]
	v_pk_mul_f32 v[94:95], v[104:105], v[94:95]
	v_pk_mul_f32 v[92:93], v[132:133], v[92:93]
	s_nop 0
	v_cvt_pk_bf16_f32 v88, v92, v93
	v_cvt_pk_bf16_f32 v89, v94, v95
	v_cvt_pk_bf16_f32 v90, v90, v91
	v_cvt_pk_bf16_f32 v91, v98, v99
	global_store_dwordx4 v96, v[88:91], s[60:61]
	s_cbranch_vccnz .LBB0_335
	s_nop 0
	v_mov_b32_e32 v88, v84
	v_mov_b32_e32 v89, v84
	v_mov_b32_e32 v92, v80
	v_mov_b32_e32 v93, v80
	v_mov_b32_e32 v90, v85
	v_mov_b32_e32 v91, v85
	v_mov_b32_e32 v97, v81
	v_mov_b32_e32 v98, v81
	v_mov_b32_e32 v94, v86
	v_mov_b32_e32 v95, v86
	v_mov_b32_e32 v101, v82
	v_mov_b32_e32 v102, v82
	v_mov_b32_e32 v99, v87
	v_mov_b32_e32 v100, v87
	v_mov_b32_e32 v103, v83
	v_mov_b32_e32 v104, v83
	v_permlane16_swap_b32_e32 v88, v89
	v_permlane16_swap_b32_e32 v92, v93
	v_permlane16_swap_b32_e32 v90, v91
	v_permlane16_swap_b32_e32 v97, v98
	v_permlane16_swap_b32_e32 v94, v95
	v_permlane16_swap_b32_e32 v101, v102
	v_permlane16_swap_b32_e32 v99, v100
	v_permlane16_swap_b32_e32 v103, v104
	s_and_saveexec_b64 s[62:63], s[10:11]
	s_cbranch_execz .LBB0_334
	v_cndmask_b32_e64 v116, v101, v102, s[44:45]
	v_cndmask_b32_e64 v102, v88, v89, s[44:45]
	v_lshl_add_u64 v[88:89], s[4:5], 0, v[216:217]
	v_cndmask_b32_e64 v114, v92, v93, s[44:45]
	v_cndmask_b32_e64 v117, v103, v104, s[44:45]
	v_cndmask_b32_e64 v103, v90, v91, s[44:45]
	v_lshl_add_u64 v[88:89], s[8:9], 0, v[216:217]
	v_cndmask_b32_e64 v115, v97, v98, s[44:45]
	v_cndmask_b32_e64 v94, v94, v95, s[44:45]
	v_cndmask_b32_e64 v95, v99, v100, s[44:45]
	v_mov_b32_e32 v104, v168
	v_mov_b32_e32 v105, v169
	v_mov_b32_e32 v106, v170
	v_mov_b32_e32 v107, v171
	v_mov_b32_e32 v90, v164
	v_mov_b32_e32 v91, v165
	v_mov_b32_e32 v92, v166
	v_mov_b32_e32 v93, v167
	v_mov_b32_e32 v108, v176
	v_mov_b32_e32 v109, v177
	v_mov_b32_e32 v110, v178
	v_mov_b32_e32 v111, v179
	v_mov_b32_e32 v98, v172
	v_mov_b32_e32 v99, v173
	v_mov_b32_e32 v100, v174
	v_mov_b32_e32 v101, v175
	v_pk_mul_f32 v[88:89], v[86:87], v[92:93]
	v_pk_mul_f32 v[90:91], v[84:85], v[90:91]
	v_pk_mul_f32 v[92:93], v[82:83], v[106:107]
	v_pk_mul_f32 v[98:99], v[98:99], v[102:103]
	v_pk_mul_f32 v[102:103], v[100:101], v[94:95]
	v_pk_mul_f32 v[94:95], v[80:81], v[104:105]
	v_pk_mul_f32 v[100:101], v[108:109], v[114:115]
	v_pk_mul_f32 v[104:105], v[110:111], v[116:117]
	s_and_saveexec_b64 s[64:65], s[42:43]
	s_xor_b64 s[68:69], exec, s[64:65]
	v_pk_add_f32 v[86:87], v[88:89], v[102:103]
	v_pk_add_f32 v[84:85], v[90:91], v[98:99]
	v_pk_add_f32 v[82:83], v[92:93], v[104:105]
	v_pk_add_f32 v[80:81], v[94:95], v[100:101]
	s_andn2_saveexec_b64 s[68:69], s[68:69]
	v_sub_f32_e32 v87, v89, v103
	v_sub_f32_e32 v86, v88, v102
	v_sub_f32_e32 v85, v91, v99
	v_sub_f32_e32 v84, v90, v98
	v_sub_f32_e32 v83, v93, v105
	v_sub_f32_e32 v82, v92, v104
	v_sub_f32_e32 v81, v95, v101
	v_sub_f32_e32 v80, v94, v100
	s_or_b64 exec, exec, s[68:69]
	s_mov_b64 s[68:69], 0x2c00

; __device__ __forceinline__ float xpart16(float v, bool oddrow) { auto r = __builtin_amdgcn_permlane16_swap(__float_as_uint(v), __float_as_uint(v), false, false); return __uint_as_float(oddrow ? r[0] : r[1]); }
; __device__ __forceinline__ unsigned cvt_pk_bf16(float lo, float hi) { unsigned r; asm volatile("v_cvt_pk_bf16_f32 %0, %1, %2" : "=v"(r) : "v"(lo), "v"(hi)); return r; }
;     __device__ __forceinline__ void operator()(f32x4 (&acc)[2][2][4][2], const Unit& u, int wr, int wc, int lane) const {
;     ...
;                 for (int bj = 0; bj < 2; ++bj) {
;                     f32x4 v0 = acc[ai][bj][m][0], v1 = acc[ai][bj][m][1];
;                     if (ropesel) {
;                         f32x4 p0, p1;
; #pragma unroll
;                         for (int j = 0; j < 4; ++j) { p0[j] = xpart16(v0[j], (fq & 1) != 0); p1[j] = xpart16(v1[j], (fq & 1) != 0); }
;                         if (rope) {
;                             const f32x4 ca = gld<f32x4>(rc, (unsigned)s * 32u), cb = gld<f32x4>(rc + 4, (unsigned)s * 32u), sa = gld<f32x4>(rs, (unsigned)s * 32u), sb = gld<f32x4>(rs + 4, (unsigned)s * 32u);
;                             if (fq == 0) { v0 = v0 * ca - p0 * sa; v1 = v1 * cb - p1 * sb; }
;                             else { v0 = v0 * ca + p0 * sa; v1 = v1 * cb + p1 * sb; }
;                         }
;                     }
;                     v0 = v0 * osc; v1 = v1 * osc;
;                     u32x4 w; w.x = cvt_pk_bf16(v0[0], v0[1]); w.y = cvt_pk_bf16(v0[2], v0[3]); w.z = cvt_pk_bf16(v1[0], v1[1]); w.w = cvt_pk_bf16(v1[2], v1[3]);
;                     gst<u32x4>(ou + bj * HALF, lo, w);
.LBB0_335:
	v_mov_b32_e32 v97, v217
	v_mov_b32_e32 v88, v132
	v_mov_b32_e32 v89, v132
	v_lshl_add_u64 v[90:91], s[60:61], 0, v[96:97]
	v_pk_mul_f32 v[92:93], v[88:89], v[82:83]
	v_pk_mul_f32 v[82:83], v[132:133], v[80:81]
	s_and_b64 vcc, exec, s[46:47]
	v_pk_mul_f32 v[86:87], v[88:89], v[86:87]
	v_pk_mul_f32 v[84:85], v[132:133], v[84:85]
	s_nop 0
	v_cvt_pk_bf16_f32 v80, v84, v85
	v_cvt_pk_bf16_f32 v81, v86, v87
	v_cvt_pk_bf16_f32 v82, v82, v83
	v_cvt_pk_bf16_f32 v83, v92, v93
	global_store_dwordx4 v[90:91], v[80:83], off offset:256
	s_cbranch_vccnz .LBB0_343
	s_nop 0
	v_mov_b32_e32 v80, v76
	v_mov_b32_e32 v81, v76
	v_mov_b32_e32 v84, v72
	v_mov_b32_e32 v85, v72
	v_mov_b32_e32 v82, v77
	v_mov_b32_e32 v83, v77
	v_mov_b32_e32 v90, v73
	v_mov_b32_e32 v91, v73
	v_mov_b32_e32 v86, v78
	v_mov_b32_e32 v87, v78
	v_mov_b32_e32 v94, v74
	v_mov_b32_e32 v95, v74
	v_mov_b32_e32 v92, v79
	v_mov_b32_e32 v93, v79
	v_mov_b32_e32 v98, v75
	v_mov_b32_e32 v99, v75
	v_permlane16_swap_b32_e32 v80, v81
	v_permlane16_swap_b32_e32 v84, v85
	v_permlane16_swap_b32_e32 v82, v83
	v_permlane16_swap_b32_e32 v90, v91
	v_permlane16_swap_b32_e32 v86, v87
	v_permlane16_swap_b32_e32 v94, v95
	v_permlane16_swap_b32_e32 v92, v93
	v_permlane16_swap_b32_e32 v98, v99
	s_and_saveexec_b64 s[62:63], s[10:11]
	s_cbranch_execz .LBB0_342
	v_cndmask_b32_e64 v108, v94, v95, s[44:45]
	v_cndmask_b32_e64 v94, v80, v81, s[44:45]
	v_lshl_add_u64 v[80:81], s[4:5], 0, v[216:217]
	v_cndmask_b32_e64 v106, v84, v85, s[44:45]
	v_cndmask_b32_e64 v109, v98, v99, s[44:45]
	v_cndmask_b32_e64 v95, v82, v83, s[44:45]
	global_load_dwordx4 v[168:171], v[218:219], off offset:16
	global_load_dwordx4 v[164:167], v[218:219], off
	global_load_dwordx4 v[176:179], v[220:221], off offset:16
	global_load_dwordx4 v[172:175], v[220:221], off
	v_lshl_add_u64 v[80:81], s[8:9], 0, v[216:217]
	v_cndmask_b32_e64 v107, v90, v91, s[44:45]
	v_cndmask_b32_e64 v86, v86, v87, s[44:45]
	v_cndmask_b32_e64 v87, v92, v93, s[44:45]
	s_waitcnt vmcnt(6)
	v_mov_b32_e32 v98, v184
	v_mov_b32_e32 v99, v185
	v_mov_b32_e32 v100, v186
	v_mov_b32_e32 v101, v187
	v_mov_b32_e32 v82, v180
	v_mov_b32_e32 v83, v181
	v_mov_b32_e32 v84, v182
	v_mov_b32_e32 v85, v183
	v_mov_b32_e32 v102, v244
	v_mov_b32_e32 v103, v245
	v_mov_b32_e32 v104, v246
	v_mov_b32_e32 v105, v247
	v_mov_b32_e32 v90, v188
	v_mov_b32_e32 v91, v189
	v_mov_b32_e32 v92, v190
	v_mov_b32_e32 v93, v191
	v_pk_mul_f32 v[80:81], v[78:79], v[84:85]
	v_pk_mul_f32 v[82:83], v[76:77], v[82:83]
	v_pk_mul_f32 v[84:85], v[74:75], v[100:101]
	v_pk_mul_f32 v[90:91], v[90:91], v[94:95]
	v_pk_mul_f32 v[94:95], v[92:93], v[86:87]
	v_pk_mul_f32 v[86:87], v[72:73], v[98:99]
	v_pk_mul_f32 v[92:93], v[102:103], v[106:107]
	v_pk_mul_f32 v[98:99], v[104:105], v[108:109]
	s_and_saveexec_b64 s[64:65], s[42:43]
	s_xor_b64 s[68:69], exec, s[64:65]
	v_pk_add_f32 v[78:79], v[80:81], v[94:95]
	v_pk_add_f32 v[76:77], v[82:83], v[90:91]
	v_pk_add_f32 v[74:75], v[84:85], v[98:99]
	v_pk_add_f32 v[72:73], v[86:87], v[92:93]
	s_andn2_saveexec_b64 s[68:69], s[68:69]
	v_sub_f32_e32 v79, v81, v95
	v_sub_f32_e32 v78, v80, v94
	v_sub_f32_e32 v77, v83, v91
	v_sub_f32_e32 v76, v82, v90
	v_sub_f32_e32 v75, v85, v99
	v_sub_f32_e32 v74, v84, v98
	v_sub_f32_e32 v73, v87, v93
	v_sub_f32_e32 v72, v86, v92
	s_or_b64 exec, exec, s[68:69]
	s_mov_b64 s[68:69], 0x2c00

; __device__ __forceinline__ float xpart16(float v, bool oddrow) { auto r = __builtin_amdgcn_permlane16_swap(__float_as_uint(v), __float_as_uint(v), false, false); return __uint_as_float(oddrow ? r[0] : r[1]); }
; __device__ __forceinline__ unsigned cvt_pk_bf16(float lo, float hi) { unsigned r; asm volatile("v_cvt_pk_bf16_f32 %0, %1, %2" : "=v"(r) : "v"(lo), "v"(hi)); return r; }
;     __device__ __forceinline__ void operator()(f32x4 (&acc)[2][2][4][2], const Unit& u, int wr, int wc, int lane) const {
;     ...
;                 for (int bj = 0; bj < 2; ++bj) {
;                     f32x4 v0 = acc[ai][bj][m][0], v1 = acc[ai][bj][m][1];
;                     if (ropesel) {
;                         f32x4 p0, p1;
; #pragma unroll
;                         for (int j = 0; j < 4; ++j) { p0[j] = xpart16(v0[j], (fq & 1) != 0); p1[j] = xpart16(v1[j], (fq & 1) != 0); }
;                         if (rope) {
;                             const f32x4 ca = gld<f32x4>(rc, (unsigned)s * 32u), cb = gld<f32x4>(rc + 4, (unsigned)s * 32u), sa = gld<f32x4>(rs, (unsigned)s * 32u), sb = gld<f32x4>(rs + 4, (unsigned)s * 32u);
;                             if (fq == 0) { v0 = v0 * ca - p0 * sa; v1 = v1 * cb - p1 * sb; }
;                             else { v0 = v0 * ca + p0 * sa; v1 = v1 * cb + p1 * sb; }
;                         }
;                     }
;                     v0 = v0 * osc; v1 = v1 * osc;
;                     u32x4 w; w.x = cvt_pk_bf16(v0[0], v0[1]); w.y = cvt_pk_bf16(v0[2], v0[3]); w.z = cvt_pk_bf16(v1[0], v1[1]); w.w = cvt_pk_bf16(v1[2], v1[3]);
;                     gst<u32x4>(ou + bj * HALF, lo, w);
.LBB0_343:
	s_nop 0
	v_add_u32_e32 v80, 0x48000, v134
	v_pk_mul_f32 v[82:83], v[88:89], v[74:75]
	v_pk_mul_f32 v[74:75], v[132:133], v[72:73]
	s_and_b64 vcc, exec, s[46:47]
	v_pk_mul_f32 v[78:79], v[88:89], v[78:79]
	v_pk_mul_f32 v[76:77], v[132:133], v[76:77]
	s_nop 0
	v_cvt_pk_bf16_f32 v72, v76, v77
	v_cvt_pk_bf16_f32 v73, v78, v79
	v_cvt_pk_bf16_f32 v74, v74, v75
	v_cvt_pk_bf16_f32 v75, v82, v83
	global_store_dwordx4 v80, v[72:75], s[60:61]
	s_cbranch_vccnz .LBB0_351
	s_nop 0
	v_mov_b32_e32 v72, v68
	v_mov_b32_e32 v73, v68
	v_mov_b32_e32 v76, v64
	v_mov_b32_e32 v77, v64
	v_mov_b32_e32 v74, v69
	v_mov_b32_e32 v75, v69
	v_mov_b32_e32 v81, v65
	v_mov_b32_e32 v82, v65
	v_mov_b32_e32 v78, v70
	v_mov_b32_e32 v79, v70
	v_mov_b32_e32 v85, v66
	v_mov_b32_e32 v86, v66
	v_mov_b32_e32 v83, v71
	v_mov_b32_e32 v84, v71
	v_mov_b32_e32 v87, v67
	v_mov_b32_e32 v88, v67
	v_permlane16_swap_b32_e32 v72, v73
	v_permlane16_swap_b32_e32 v76, v77
	v_permlane16_swap_b32_e32 v74, v75
	v_permlane16_swap_b32_e32 v81, v82
	v_permlane16_swap_b32_e32 v78, v79
	v_permlane16_swap_b32_e32 v85, v86
	v_permlane16_swap_b32_e32 v83, v84
	v_permlane16_swap_b32_e32 v87, v88
	s_and_saveexec_b64 s[62:63], s[10:11]
	s_cbranch_execz .LBB0_350
	v_cndmask_b32_e64 v100, v85, v86, s[44:45]
	v_cndmask_b32_e64 v86, v72, v73, s[44:45]
	v_lshl_add_u64 v[72:73], s[4:5], 0, v[216:217]
	v_cndmask_b32_e64 v98, v76, v77, s[44:45]
	v_cndmask_b32_e64 v101, v87, v88, s[44:45]
	v_cndmask_b32_e64 v87, v74, v75, s[44:45]
	v_lshl_add_u64 v[72:73], s[8:9], 0, v[216:217]
	v_cndmask_b32_e64 v99, v81, v82, s[44:45]
	v_cndmask_b32_e64 v78, v78, v79, s[44:45]
	v_cndmask_b32_e64 v79, v83, v84, s[44:45]
	v_mov_b32_e32 v88, v184
	v_mov_b32_e32 v89, v185
	v_mov_b32_e32 v90, v186
	v_mov_b32_e32 v91, v187
	v_mov_b32_e32 v74, v180
	v_mov_b32_e32 v75, v181
	v_mov_b32_e32 v76, v182
	v_mov_b32_e32 v77, v183
	v_mov_b32_e32 v92, v244
	v_mov_b32_e32 v93, v245
	v_mov_b32_e32 v94, v246
	v_mov_b32_e32 v95, v247
	v_mov_b32_e32 v82, v188
	v_mov_b32_e32 v83, v189
	v_mov_b32_e32 v84, v190
	v_mov_b32_e32 v85, v191
	v_pk_mul_f32 v[72:73], v[70:71], v[76:77]
	v_pk_mul_f32 v[74:75], v[68:69], v[74:75]
	v_pk_mul_f32 v[76:77], v[66:67], v[90:91]
	v_pk_mul_f32 v[82:83], v[82:83], v[86:87]
	v_pk_mul_f32 v[86:87], v[84:85], v[78:79]
	v_pk_mul_f32 v[78:79], v[64:65], v[88:89]
	v_pk_mul_f32 v[84:85], v[92:93], v[98:99]
	v_pk_mul_f32 v[88:89], v[94:95], v[100:101]
	s_and_saveexec_b64 s[64:65], s[42:43]
	s_xor_b64 s[68:69], exec, s[64:65]
	v_pk_add_f32 v[70:71], v[72:73], v[86:87]
	v_pk_add_f32 v[68:69], v[74:75], v[82:83]
	v_pk_add_f32 v[66:67], v[76:77], v[88:89]
	v_pk_add_f32 v[64:65], v[78:79], v[84:85]
	s_andn2_saveexec_b64 s[68:69], s[68:69]
	v_sub_f32_e32 v71, v73, v87
	v_sub_f32_e32 v70, v72, v86
	v_sub_f32_e32 v69, v75, v83
	v_sub_f32_e32 v68, v74, v82
	v_sub_f32_e32 v67, v77, v89
	v_sub_f32_e32 v66, v76, v88
	v_sub_f32_e32 v65, v79, v85
	v_sub_f32_e32 v64, v78, v84
	s_or_b64 exec, exec, s[68:69]
	s_mov_b64 s[68:69], 0x2c00

; __device__ __forceinline__ float xpart16(float v, bool oddrow) { auto r = __builtin_amdgcn_permlane16_swap(__float_as_uint(v), __float_as_uint(v), false, false); return __uint_as_float(oddrow ? r[0] : r[1]); }
; __device__ __forceinline__ unsigned cvt_pk_bf16(float lo, float hi) { unsigned r; asm volatile("v_cvt_pk_bf16_f32 %0, %1, %2" : "=v"(r) : "v"(lo), "v"(hi)); return r; }
;     __device__ __forceinline__ void operator()(f32x4 (&acc)[2][2][4][2], const Unit& u, int wr, int wc, int lane) const {
;     ...
;                 for (int bj = 0; bj < 2; ++bj) {
;                     f32x4 v0 = acc[ai][bj][m][0], v1 = acc[ai][bj][m][1];
;                     if (ropesel) {
;                         f32x4 p0, p1;
; #pragma unroll
;                         for (int j = 0; j < 4; ++j) { p0[j] = xpart16(v0[j], (fq & 1) != 0); p1[j] = xpart16(v1[j], (fq & 1) != 0); }
;                         if (rope) {
;                             const f32x4 ca = gld<f32x4>(rc, (unsigned)s * 32u), cb = gld<f32x4>(rc + 4, (unsigned)s * 32u), sa = gld<f32x4>(rs, (unsigned)s * 32u), sb = gld<f32x4>(rs + 4, (unsigned)s * 32u);
;                             if (fq == 0) { v0 = v0 * ca - p0 * sa; v1 = v1 * cb - p1 * sb; }
;                             else { v0 = v0 * ca + p0 * sa; v1 = v1 * cb + p1 * sb; }
;                         }
;                     }
;                     v0 = v0 * osc; v1 = v1 * osc;
;                     u32x4 w; w.x = cvt_pk_bf16(v0[0], v0[1]); w.y = cvt_pk_bf16(v0[2], v0[3]); w.z = cvt_pk_bf16(v1[0], v1[1]); w.w = cvt_pk_bf16(v1[2], v1[3]);
;                     gst<u32x4>(ou + bj * HALF, lo, w);
.LBB0_351:
	v_mov_b32_e32 v81, v217
	v_mov_b32_e32 v72, v132
	v_mov_b32_e32 v73, v132
	s_addk_i32 s23, 0x80
	v_lshl_add_u64 v[74:75], s[60:61], 0, v[80:81]
	v_pk_mul_f32 v[68:69], v[132:133], v[68:69]
	v_pk_mul_f32 v[76:77], v[72:73], v[66:67]
	v_pk_mul_f32 v[66:67], v[132:133], v[64:65]
	v_cvt_pk_bf16_f32 v64, v68, v69
	s_and_b32 s39, s23, 0xfc0
	v_pk_mul_f32 v[70:71], v[72:73], v[70:71]
	s_and_b64 vcc, exec, s[46:47]
	v_cvt_pk_bf16_f32 v65, v70, v71
	v_cvt_pk_bf16_f32 v66, v66, v67
	v_cvt_pk_bf16_f32 v67, v76, v77
	global_store_dwordx4 v[74:75], v[64:67], off offset:256
	s_nop 1
	v_or_b32_e32 v64, s39, v150
	v_lshlrev_b32_e32 v216, 5, v64
	s_cbranch_vccnz .LBB0_359
	v_mov_b32_e32 v64, v60
	v_mov_b32_e32 v65, v60
	v_mov_b32_e32 v68, v56
	v_mov_b32_e32 v69, v56
	v_mov_b32_e32 v66, v61
	v_mov_b32_e32 v67, v61
	v_mov_b32_e32 v74, v57
	v_mov_b32_e32 v75, v57
	v_mov_b32_e32 v70, v62
	v_mov_b32_e32 v71, v62
	v_mov_b32_e32 v78, v58
	v_mov_b32_e32 v79, v58
	v_mov_b32_e32 v76, v63
	v_mov_b32_e32 v77, v63
	v_mov_b32_e32 v82, v59
	v_mov_b32_e32 v83, v59
	v_permlane16_swap_b32_e32 v64, v65
	v_permlane16_swap_b32_e32 v68, v69
	v_permlane16_swap_b32_e32 v66, v67
	v_permlane16_swap_b32_e32 v74, v75
	v_permlane16_swap_b32_e32 v70, v71
	v_permlane16_swap_b32_e32 v78, v79
	v_permlane16_swap_b32_e32 v76, v77
	v_permlane16_swap_b32_e32 v82, v83
	s_and_saveexec_b64 s[60:61], s[10:11]
	s_cbranch_execz .LBB0_358
	v_cndmask_b32_e64 v92, v78, v79, s[44:45]
	v_cndmask_b32_e64 v78, v64, v65, s[44:45]
	v_lshl_add_u64 v[64:65], s[4:5], 0, v[216:217]
	v_cndmask_b32_e64 v90, v68, v69, s[44:45]
	v_cndmask_b32_e64 v93, v82, v83, s[44:45]
	v_cndmask_b32_e64 v79, v66, v67, s[44:45]
	global_load_dwordx4 v[184:187], v[218:219], off offset:528
	global_load_dwordx4 v[180:183], v[218:219], off offset:512
	global_load_dwordx4 v[244:247], v[220:221], off offset:528
	global_load_dwordx4 v[188:191], v[220:221], off offset:512
	v_lshl_add_u64 v[64:65], s[8:9], 0, v[216:217]
	v_cndmask_b32_e64 v91, v74, v75, s[44:45]
	v_cndmask_b32_e64 v70, v70, v71, s[44:45]
	v_cndmask_b32_e64 v71, v76, v77, s[44:45]
	s_waitcnt vmcnt(6)
	v_mov_b32_e32 v82, v168
	v_mov_b32_e32 v83, v169
	v_mov_b32_e32 v84, v170
	v_mov_b32_e32 v85, v171
	v_mov_b32_e32 v66, v164
	v_mov_b32_e32 v67, v165
	v_mov_b32_e32 v68, v166
	v_mov_b32_e32 v69, v167
	v_mov_b32_e32 v86, v176
	v_mov_b32_e32 v87, v177
	v_mov_b32_e32 v88, v178
	v_mov_b32_e32 v89, v179
	v_mov_b32_e32 v74, v172
	v_mov_b32_e32 v75, v173
	v_mov_b32_e32 v76, v174
	v_mov_b32_e32 v77, v175
	v_pk_mul_f32 v[64:65], v[62:63], v[68:69]
	v_pk_mul_f32 v[66:67], v[60:61], v[66:67]
	v_pk_mul_f32 v[68:69], v[58:59], v[84:85]
	v_pk_mul_f32 v[74:75], v[74:75], v[78:79]
	v_pk_mul_f32 v[78:79], v[76:77], v[70:71]
	v_pk_mul_f32 v[70:71], v[56:57], v[82:83]
	v_pk_mul_f32 v[76:77], v[86:87], v[90:91]
	v_pk_mul_f32 v[82:83], v[88:89], v[92:93]
	s_and_saveexec_b64 s[62:63], s[42:43]
	s_xor_b64 s[62:63], exec, s[62:63]
	v_pk_add_f32 v[62:63], v[64:65], v[78:79]
	v_pk_add_f32 v[60:61], v[66:67], v[74:75]
	v_pk_add_f32 v[58:59], v[68:69], v[82:83]
	v_pk_add_f32 v[56:57], v[70:71], v[76:77]
	s_andn2_saveexec_b64 s[62:63], s[62:63]
	v_sub_f32_e32 v63, v65, v79
	v_sub_f32_e32 v62, v64, v78
	v_sub_f32_e32 v61, v67, v75
	v_sub_f32_e32 v60, v66, v74
	v_sub_f32_e32 v59, v69, v83
	v_sub_f32_e32 v58, v68, v82
	v_sub_f32_e32 v57, v71, v77
	v_sub_f32_e32 v56, v70, v76
	s_or_b64 exec, exec, s[62:63]

; __device__ __forceinline__ float xpart16(float v, bool oddrow) { auto r = __builtin_amdgcn_permlane16_swap(__float_as_uint(v), __float_as_uint(v), false, false); return __uint_as_float(oddrow ? r[0] : r[1]); }
; __device__ __forceinline__ unsigned cvt_pk_bf16(float lo, float hi) { unsigned r; asm volatile("v_cvt_pk_bf16_f32 %0, %1, %2" : "=v"(r) : "v"(lo), "v"(hi)); return r; }
;     __device__ __forceinline__ void operator()(f32x4 (&acc)[2][2][4][2], const Unit& u, int wr, int wc, int lane) const {
;     ...
;                 for (int bj = 0; bj < 2; ++bj) {
;                     f32x4 v0 = acc[ai][bj][m][0], v1 = acc[ai][bj][m][1];
;                     if (ropesel) {
;                         f32x4 p0, p1;
; #pragma unroll
;                         for (int j = 0; j < 4; ++j) { p0[j] = xpart16(v0[j], (fq & 1) != 0); p1[j] = xpart16(v1[j], (fq & 1) != 0); }
;                         if (rope) {
;                             const f32x4 ca = gld<f32x4>(rc, (unsigned)s * 32u), cb = gld<f32x4>(rc + 4, (unsigned)s * 32u), sa = gld<f32x4>(rs, (unsigned)s * 32u), sb = gld<f32x4>(rs + 4, (unsigned)s * 32u);
;                             if (fq == 0) { v0 = v0 * ca - p0 * sa; v1 = v1 * cb - p1 * sb; }
;                             else { v0 = v0 * ca + p0 * sa; v1 = v1 * cb + p1 * sb; }
;                         }
;                     }
;                     v0 = v0 * osc; v1 = v1 * osc;
;                     u32x4 w; w.x = cvt_pk_bf16(v0[0], v0[1]); w.y = cvt_pk_bf16(v0[2], v0[3]); w.z = cvt_pk_bf16(v1[0], v1[1]); w.w = cvt_pk_bf16(v1[2], v1[3]);
;                     gst<u32x4>(ou + bj * HALF, lo, w);
.LBB0_359:
	s_mul_hi_i32 s39, s23, 0x1800
	s_mulk_i32 s23, 0x1800
	s_add_u32 s23, s30, s23
	s_addc_u32 s39, s31, s39
	s_add_u32 s23, s23, s58
	s_addc_u32 s39, s39, s59
	s_add_u32 s58, s23, s37
	s_addc_u32 s59, s39, 0
	v_lshl_add_u64 v[64:65], s[58:59], 0, v[134:135]
	v_pk_mul_f32 v[66:67], v[72:73], v[58:59]
	v_pk_mul_f32 v[58:59], v[132:133], v[56:57]
	s_and_b64 vcc, exec, s[46:47]
	v_pk_mul_f32 v[62:63], v[72:73], v[62:63]
	v_pk_mul_f32 v[60:61], v[132:133], v[60:61]
	s_nop 0
	v_cvt_pk_bf16_f32 v56, v60, v61
	v_cvt_pk_bf16_f32 v57, v62, v63
	v_cvt_pk_bf16_f32 v58, v58, v59
	v_cvt_pk_bf16_f32 v59, v66, v67
	global_store_dwordx4 v[64:65], v[56:59], off
	s_cbranch_vccnz .LBB0_367
	s_nop 0
	v_mov_b32_e32 v56, v52
	v_mov_b32_e32 v57, v52
	v_mov_b32_e32 v60, v48
	v_mov_b32_e32 v61, v48
	v_mov_b32_e32 v58, v53
	v_mov_b32_e32 v59, v53
	v_mov_b32_e32 v66, v49
	v_mov_b32_e32 v67, v49
	v_mov_b32_e32 v62, v54
	v_mov_b32_e32 v63, v54
	v_mov_b32_e32 v70, v50
	v_mov_b32_e32 v71, v50
	v_mov_b32_e32 v68, v55
	v_mov_b32_e32 v69, v55
	v_mov_b32_e32 v72, v51
	v_mov_b32_e32 v73, v51
	v_permlane16_swap_b32_e32 v56, v57
	v_permlane16_swap_b32_e32 v60, v61
	v_permlane16_swap_b32_e32 v58, v59
	v_permlane16_swap_b32_e32 v66, v67
	v_permlane16_swap_b32_e32 v62, v63
	v_permlane16_swap_b32_e32 v70, v71
	v_permlane16_swap_b32_e32 v68, v69
	v_permlane16_swap_b32_e32 v72, v73
	s_and_saveexec_b64 s[60:61], s[10:11]
	s_cbranch_execz .LBB0_366
	v_cndmask_b32_e64 v84, v70, v71, s[44:45]
	v_cndmask_b32_e64 v70, v56, v57, s[44:45]
	v_lshl_add_u64 v[56:57], s[4:5], 0, v[216:217]
	v_cndmask_b32_e64 v82, v60, v61, s[44:45]
	v_cndmask_b32_e64 v85, v72, v73, s[44:45]
	v_cndmask_b32_e64 v71, v58, v59, s[44:45]
	v_lshl_add_u64 v[56:57], s[8:9], 0, v[216:217]
	v_cndmask_b32_e64 v83, v66, v67, s[44:45]
	v_cndmask_b32_e64 v62, v62, v63, s[44:45]
	v_cndmask_b32_e64 v63, v68, v69, s[44:45]
	v_mov_b32_e32 v72, v168
	v_mov_b32_e32 v73, v169
	v_mov_b32_e32 v74, v170
	v_mov_b32_e32 v75, v171
	v_mov_b32_e32 v58, v164
	v_mov_b32_e32 v59, v165
	v_mov_b32_e32 v60, v166
	v_mov_b32_e32 v61, v167
	v_mov_b32_e32 v76, v176
	v_mov_b32_e32 v77, v177
	v_mov_b32_e32 v78, v178
	v_mov_b32_e32 v79, v179
	v_mov_b32_e32 v66, v172
	v_mov_b32_e32 v67, v173
	v_mov_b32_e32 v68, v174
	v_mov_b32_e32 v69, v175
	v_pk_mul_f32 v[56:57], v[54:55], v[60:61]
	v_pk_mul_f32 v[58:59], v[52:53], v[58:59]
	v_pk_mul_f32 v[60:61], v[50:51], v[74:75]
	v_pk_mul_f32 v[66:67], v[66:67], v[70:71]
	v_pk_mul_f32 v[70:71], v[68:69], v[62:63]
	v_pk_mul_f32 v[62:63], v[48:49], v[72:73]
	v_pk_mul_f32 v[68:69], v[76:77], v[82:83]
	v_pk_mul_f32 v[72:73], v[78:79], v[84:85]
	s_and_saveexec_b64 s[62:63], s[42:43]
	s_xor_b64 s[62:63], exec, s[62:63]
	v_pk_add_f32 v[54:55], v[56:57], v[70:71]
	v_pk_add_f32 v[52:53], v[58:59], v[66:67]
	v_pk_add_f32 v[50:51], v[60:61], v[72:73]
	v_pk_add_f32 v[48:49], v[62:63], v[68:69]
	s_andn2_saveexec_b64 s[62:63], s[62:63]
	v_sub_f32_e32 v55, v57, v71
	v_sub_f32_e32 v54, v56, v70
	v_sub_f32_e32 v53, v59, v67
	v_sub_f32_e32 v52, v58, v66
	v_sub_f32_e32 v51, v61, v73
	v_sub_f32_e32 v50, v60, v72
	v_sub_f32_e32 v49, v63, v69
	v_sub_f32_e32 v48, v62, v68
	s_or_b64 exec, exec, s[62:63]

; __device__ __forceinline__ float xpart16(float v, bool oddrow) { auto r = __builtin_amdgcn_permlane16_swap(__float_as_uint(v), __float_as_uint(v), false, false); return __uint_as_float(oddrow ? r[0] : r[1]); }
; __device__ __forceinline__ unsigned cvt_pk_bf16(float lo, float hi) { unsigned r; asm volatile("v_cvt_pk_bf16_f32 %0, %1, %2" : "=v"(r) : "v"(lo), "v"(hi)); return r; }
;     __device__ __forceinline__ void operator()(f32x4 (&acc)[2][2][4][2], const Unit& u, int wr, int wc, int lane) const {
;     ...
;                 for (int bj = 0; bj < 2; ++bj) {
;                     f32x4 v0 = acc[ai][bj][m][0], v1 = acc[ai][bj][m][1];
;                     if (ropesel) {
;                         f32x4 p0, p1;
; #pragma unroll
;                         for (int j = 0; j < 4; ++j) { p0[j] = xpart16(v0[j], (fq & 1) != 0); p1[j] = xpart16(v1[j], (fq & 1) != 0); }
;                         if (rope) {
;                             const f32x4 ca = gld<f32x4>(rc, (unsigned)s * 32u), cb = gld<f32x4>(rc + 4, (unsigned)s * 32u), sa = gld<f32x4>(rs, (unsigned)s * 32u), sb = gld<f32x4>(rs + 4, (unsigned)s * 32u);
;                             if (fq == 0) { v0 = v0 * ca - p0 * sa; v1 = v1 * cb - p1 * sb; }
;                             else { v0 = v0 * ca + p0 * sa; v1 = v1 * cb + p1 * sb; }
;                         }
;                     }
;                     v0 = v0 * osc; v1 = v1 * osc;
;                     u32x4 w; w.x = cvt_pk_bf16(v0[0], v0[1]); w.y = cvt_pk_bf16(v0[2], v0[3]); w.z = cvt_pk_bf16(v1[0], v1[1]); w.w = cvt_pk_bf16(v1[2], v1[3]);
;                     gst<u32x4>(ou + bj * HALF, lo, w);
.LBB0_367:
	s_nop 0
	v_mov_b32_e32 v56, v132
	v_mov_b32_e32 v57, v132
	v_pk_mul_f32 v[58:59], v[56:57], v[50:51]
	v_pk_mul_f32 v[50:51], v[132:133], v[48:49]
	s_and_b64 vcc, exec, s[46:47]
	v_pk_mul_f32 v[54:55], v[56:57], v[54:55]
	v_pk_mul_f32 v[52:53], v[132:133], v[52:53]
	s_nop 0
	v_cvt_pk_bf16_f32 v48, v52, v53
	v_cvt_pk_bf16_f32 v49, v54, v55
	v_cvt_pk_bf16_f32 v50, v50, v51
	v_cvt_pk_bf16_f32 v51, v58, v59
	global_store_dwordx4 v[64:65], v[48:51], off offset:256
	s_cbranch_vccnz .LBB0_375
	s_nop 0
	v_mov_b32_e32 v48, v44
	v_mov_b32_e32 v49, v44
	v_mov_b32_e32 v52, v40
	v_mov_b32_e32 v53, v40
	v_mov_b32_e32 v50, v45
	v_mov_b32_e32 v51, v45
	v_mov_b32_e32 v58, v41
	v_mov_b32_e32 v59, v41
	v_mov_b32_e32 v54, v46
	v_mov_b32_e32 v55, v46
	v_mov_b32_e32 v62, v42
	v_mov_b32_e32 v63, v42
	v_mov_b32_e32 v60, v47
	v_mov_b32_e32 v61, v47
	v_mov_b32_e32 v64, v43
	v_mov_b32_e32 v65, v43
	v_permlane16_swap_b32_e32 v48, v49
	v_permlane16_swap_b32_e32 v52, v53
	v_permlane16_swap_b32_e32 v50, v51
	v_permlane16_swap_b32_e32 v58, v59
	v_permlane16_swap_b32_e32 v54, v55
	v_permlane16_swap_b32_e32 v62, v63
	v_permlane16_swap_b32_e32 v60, v61
	v_permlane16_swap_b32_e32 v64, v65
	s_and_saveexec_b64 s[60:61], s[10:11]
	s_cbranch_execz .LBB0_374
	v_cndmask_b32_e64 v74, v62, v63, s[44:45]
	v_cndmask_b32_e64 v62, v48, v49, s[44:45]
	v_lshl_add_u64 v[48:49], s[4:5], 0, v[216:217]
	v_cndmask_b32_e64 v72, v52, v53, s[44:45]
	v_cndmask_b32_e64 v75, v64, v65, s[44:45]
	v_cndmask_b32_e64 v63, v50, v51, s[44:45]
	global_load_dwordx4 v[168:171], v[218:219], off offset:1040
	global_load_dwordx4 v[164:167], v[218:219], off offset:1024
	global_load_dwordx4 v[176:179], v[220:221], off offset:1040
	global_load_dwordx4 v[172:175], v[220:221], off offset:1024
	v_lshl_add_u64 v[48:49], s[8:9], 0, v[216:217]
	v_cndmask_b32_e64 v73, v58, v59, s[44:45]
	v_cndmask_b32_e64 v54, v54, v55, s[44:45]
	v_cndmask_b32_e64 v55, v60, v61, s[44:45]
	s_waitcnt vmcnt(6)
	v_mov_b32_e32 v64, v184
	v_mov_b32_e32 v65, v185
	v_mov_b32_e32 v66, v186
	v_mov_b32_e32 v67, v187
	v_mov_b32_e32 v50, v180
	v_mov_b32_e32 v51, v181
	v_mov_b32_e32 v52, v182
	v_mov_b32_e32 v53, v183
	v_mov_b32_e32 v68, v244
	v_mov_b32_e32 v69, v245
	v_mov_b32_e32 v70, v246
	v_mov_b32_e32 v71, v247
	v_mov_b32_e32 v58, v188
	v_mov_b32_e32 v59, v189
	v_mov_b32_e32 v60, v190
	v_mov_b32_e32 v61, v191
	v_pk_mul_f32 v[48:49], v[46:47], v[52:53]
	v_pk_mul_f32 v[50:51], v[44:45], v[50:51]
	v_pk_mul_f32 v[52:53], v[42:43], v[66:67]
	v_pk_mul_f32 v[58:59], v[58:59], v[62:63]
	v_pk_mul_f32 v[62:63], v[60:61], v[54:55]
	v_pk_mul_f32 v[54:55], v[40:41], v[64:65]
	v_pk_mul_f32 v[60:61], v[68:69], v[72:73]
	v_pk_mul_f32 v[64:65], v[70:71], v[74:75]
	s_and_saveexec_b64 s[62:63], s[42:43]
	s_xor_b64 s[62:63], exec, s[62:63]
	v_pk_add_f32 v[46:47], v[48:49], v[62:63]
	v_pk_add_f32 v[44:45], v[50:51], v[58:59]
	v_pk_add_f32 v[42:43], v[52:53], v[64:65]
	v_pk_add_f32 v[40:41], v[54:55], v[60:61]
	s_andn2_saveexec_b64 s[62:63], s[62:63]
	v_sub_f32_e32 v47, v49, v63
	v_sub_f32_e32 v46, v48, v62
	v_sub_f32_e32 v45, v51, v59
	v_sub_f32_e32 v44, v50, v58
	v_sub_f32_e32 v43, v53, v65
	v_sub_f32_e32 v42, v52, v64
	v_sub_f32_e32 v41, v55, v61
	v_sub_f32_e32 v40, v54, v60
	s_or_b64 exec, exec, s[62:63]

; __device__ __forceinline__ float xpart16(float v, bool oddrow) { auto r = __builtin_amdgcn_permlane16_swap(__float_as_uint(v), __float_as_uint(v), false, false); return __uint_as_float(oddrow ? r[0] : r[1]); }
; __device__ __forceinline__ unsigned cvt_pk_bf16(float lo, float hi) { unsigned r; asm volatile("v_cvt_pk_bf16_f32 %0, %1, %2" : "=v"(r) : "v"(lo), "v"(hi)); return r; }
;     __device__ __forceinline__ void operator()(f32x4 (&acc)[2][2][4][2], const Unit& u, int wr, int wc, int lane) const {
;     ...
;                 for (int bj = 0; bj < 2; ++bj) {
;                     f32x4 v0 = acc[ai][bj][m][0], v1 = acc[ai][bj][m][1];
;                     if (ropesel) {
;                         f32x4 p0, p1;
; #pragma unroll
;                         for (int j = 0; j < 4; ++j) { p0[j] = xpart16(v0[j], (fq & 1) != 0); p1[j] = xpart16(v1[j], (fq & 1) != 0); }
;                         if (rope) {
;                             const f32x4 ca = gld<f32x4>(rc, (unsigned)s * 32u), cb = gld<f32x4>(rc + 4, (unsigned)s * 32u), sa = gld<f32x4>(rs, (unsigned)s * 32u), sb = gld<f32x4>(rs + 4, (unsigned)s * 32u);
;                             if (fq == 0) { v0 = v0 * ca - p0 * sa; v1 = v1 * cb - p1 * sb; }
;                             else { v0 = v0 * ca + p0 * sa; v1 = v1 * cb + p1 * sb; }
;                         }
;                     }
;                     v0 = v0 * osc; v1 = v1 * osc;
;                     u32x4 w; w.x = cvt_pk_bf16(v0[0], v0[1]); w.y = cvt_pk_bf16(v0[2], v0[3]); w.z = cvt_pk_bf16(v1[0], v1[1]); w.w = cvt_pk_bf16(v1[2], v1[3]);
;                     gst<u32x4>(ou + bj * HALF, lo, w);
.LBB0_375:
	s_nop 0
	v_lshl_add_u64 v[48:49], s[58:59], 0, v[112:113]
	v_pk_mul_f32 v[50:51], v[56:57], v[42:43]
	v_pk_mul_f32 v[42:43], v[132:133], v[40:41]
	s_and_b64 vcc, exec, s[46:47]
	v_pk_mul_f32 v[46:47], v[56:57], v[46:47]
	v_pk_mul_f32 v[44:45], v[132:133], v[44:45]
	s_nop 0
	v_cvt_pk_bf16_f32 v40, v44, v45
	v_cvt_pk_bf16_f32 v41, v46, v47
	v_cvt_pk_bf16_f32 v42, v42, v43
	v_cvt_pk_bf16_f32 v43, v50, v51
	global_store_dwordx4 v[48:49], v[40:43], off
	s_cbranch_vccnz .LBB0_383
	s_nop 0
	v_mov_b32_e32 v40, v36
	v_mov_b32_e32 v41, v36
	v_mov_b32_e32 v44, v32
	v_mov_b32_e32 v45, v32
	v_mov_b32_e32 v42, v37
	v_mov_b32_e32 v43, v37
	v_mov_b32_e32 v50, v33
	v_mov_b32_e32 v51, v33
	v_mov_b32_e32 v46, v38
	v_mov_b32_e32 v47, v38
	v_mov_b32_e32 v54, v34
	v_mov_b32_e32 v55, v34
	v_mov_b32_e32 v52, v39
	v_mov_b32_e32 v53, v39
	v_mov_b32_e32 v56, v35
	v_mov_b32_e32 v57, v35
	v_permlane16_swap_b32_e32 v40, v41
	v_permlane16_swap_b32_e32 v44, v45
	v_permlane16_swap_b32_e32 v42, v43
	v_permlane16_swap_b32_e32 v50, v51
	v_permlane16_swap_b32_e32 v46, v47
	v_permlane16_swap_b32_e32 v54, v55
	v_permlane16_swap_b32_e32 v52, v53
	v_permlane16_swap_b32_e32 v56, v57
	s_and_saveexec_b64 s[60:61], s[10:11]
	s_cbranch_execz .LBB0_382
	v_cndmask_b32_e64 v66, v54, v55, s[44:45]
	v_cndmask_b32_e64 v54, v40, v41, s[44:45]
	v_lshl_add_u64 v[40:41], s[4:5], 0, v[216:217]
	v_cndmask_b32_e64 v64, v44, v45, s[44:45]
	v_cndmask_b32_e64 v67, v56, v57, s[44:45]
	v_cndmask_b32_e64 v55, v42, v43, s[44:45]
	v_lshl_add_u64 v[40:41], s[8:9], 0, v[216:217]
	v_cndmask_b32_e64 v65, v50, v51, s[44:45]
	v_cndmask_b32_e64 v46, v46, v47, s[44:45]
	v_cndmask_b32_e64 v47, v52, v53, s[44:45]
	v_mov_b32_e32 v56, v184
	v_mov_b32_e32 v57, v185
	v_mov_b32_e32 v58, v186
	v_mov_b32_e32 v59, v187
	v_mov_b32_e32 v42, v180
	v_mov_b32_e32 v43, v181
	v_mov_b32_e32 v44, v182
	v_mov_b32_e32 v45, v183
	v_mov_b32_e32 v60, v244
	v_mov_b32_e32 v61, v245
	v_mov_b32_e32 v62, v246
	v_mov_b32_e32 v63, v247
	v_mov_b32_e32 v50, v188
	v_mov_b32_e32 v51, v189
	v_mov_b32_e32 v52, v190
	v_mov_b32_e32 v53, v191
	v_pk_mul_f32 v[40:41], v[38:39], v[44:45]
	v_pk_mul_f32 v[42:43], v[36:37], v[42:43]
	v_pk_mul_f32 v[44:45], v[34:35], v[58:59]
	v_pk_mul_f32 v[50:51], v[50:51], v[54:55]
	v_pk_mul_f32 v[54:55], v[52:53], v[46:47]
	v_pk_mul_f32 v[46:47], v[32:33], v[56:57]
	v_pk_mul_f32 v[52:53], v[60:61], v[64:65]
	v_pk_mul_f32 v[56:57], v[62:63], v[66:67]
	s_and_saveexec_b64 s[62:63], s[42:43]
	s_xor_b64 s[62:63], exec, s[62:63]
	v_pk_add_f32 v[38:39], v[40:41], v[54:55]
	v_pk_add_f32 v[36:37], v[42:43], v[50:51]
	v_pk_add_f32 v[34:35], v[44:45], v[56:57]
	v_pk_add_f32 v[32:33], v[46:47], v[52:53]
	s_andn2_saveexec_b64 s[62:63], s[62:63]
	v_sub_f32_e32 v39, v41, v55
	v_sub_f32_e32 v38, v40, v54
	v_sub_f32_e32 v37, v43, v51
	v_sub_f32_e32 v36, v42, v50
	v_sub_f32_e32 v35, v45, v57
	v_sub_f32_e32 v34, v44, v56
	v_sub_f32_e32 v33, v47, v53
	v_sub_f32_e32 v32, v46, v52
	s_or_b64 exec, exec, s[62:63]

; __device__ __forceinline__ float xpart16(float v, bool oddrow) { auto r = __builtin_amdgcn_permlane16_swap(__float_as_uint(v), __float_as_uint(v), false, false); return __uint_as_float(oddrow ? r[0] : r[1]); }
; __device__ __forceinline__ unsigned cvt_pk_bf16(float lo, float hi) { unsigned r; asm volatile("v_cvt_pk_bf16_f32 %0, %1, %2" : "=v"(r) : "v"(lo), "v"(hi)); return r; }
;     __device__ __forceinline__ void operator()(f32x4 (&acc)[2][2][4][2], const Unit& u, int wr, int wc, int lane) const {
;     ...
;                 for (int bj = 0; bj < 2; ++bj) {
;                     f32x4 v0 = acc[ai][bj][m][0], v1 = acc[ai][bj][m][1];
;                     if (ropesel) {
;                         f32x4 p0, p1;
; #pragma unroll
;                         for (int j = 0; j < 4; ++j) { p0[j] = xpart16(v0[j], (fq & 1) != 0); p1[j] = xpart16(v1[j], (fq & 1) != 0); }
;                         if (rope) {
;                             const f32x4 ca = gld<f32x4>(rc, (unsigned)s * 32u), cb = gld<f32x4>(rc + 4, (unsigned)s * 32u), sa = gld<f32x4>(rs, (unsigned)s * 32u), sb = gld<f32x4>(rs + 4, (unsigned)s * 32u);
;                             if (fq == 0) { v0 = v0 * ca - p0 * sa; v1 = v1 * cb - p1 * sb; }
;                             else { v0 = v0 * ca + p0 * sa; v1 = v1 * cb + p1 * sb; }
;                         }
;                     }
;                     v0 = v0 * osc; v1 = v1 * osc;
;                     u32x4 w; w.x = cvt_pk_bf16(v0[0], v0[1]); w.y = cvt_pk_bf16(v0[2], v0[3]); w.z = cvt_pk_bf16(v1[0], v1[1]); w.w = cvt_pk_bf16(v1[2], v1[3]);
;                     gst<u32x4>(ou + bj * HALF, lo, w);
.LBB0_383:
	s_nop 0
	v_mov_b32_e32 v40, v132
	v_mov_b32_e32 v41, v132
	v_pk_mul_f32 v[42:43], v[40:41], v[34:35]
	v_pk_mul_f32 v[34:35], v[132:133], v[32:33]
	s_and_b64 vcc, exec, s[46:47]
	v_pk_mul_f32 v[38:39], v[40:41], v[38:39]
	v_pk_mul_f32 v[36:37], v[132:133], v[36:37]
	s_nop 0
	v_cvt_pk_bf16_f32 v32, v36, v37
	v_cvt_pk_bf16_f32 v33, v38, v39
	v_cvt_pk_bf16_f32 v34, v34, v35
	v_cvt_pk_bf16_f32 v35, v42, v43
	global_store_dwordx4 v[48:49], v[32:35], off offset:256
	s_cbranch_vccnz .LBB0_391
	s_nop 0
	v_mov_b32_e32 v32, v28
	v_mov_b32_e32 v33, v28
	v_mov_b32_e32 v36, v24
	v_mov_b32_e32 v37, v24
	v_mov_b32_e32 v34, v29
	v_mov_b32_e32 v35, v29
	v_mov_b32_e32 v42, v25
	v_mov_b32_e32 v43, v25
	v_mov_b32_e32 v38, v30
	v_mov_b32_e32 v39, v30
	v_mov_b32_e32 v46, v26
	v_mov_b32_e32 v47, v26
	v_mov_b32_e32 v44, v31
	v_mov_b32_e32 v45, v31
	v_mov_b32_e32 v48, v27
	v_mov_b32_e32 v49, v27
	v_permlane16_swap_b32_e32 v32, v33
	v_permlane16_swap_b32_e32 v36, v37
	v_permlane16_swap_b32_e32 v34, v35
	v_permlane16_swap_b32_e32 v42, v43
	v_permlane16_swap_b32_e32 v38, v39
	v_permlane16_swap_b32_e32 v46, v47
	v_permlane16_swap_b32_e32 v44, v45
	v_permlane16_swap_b32_e32 v48, v49
	s_and_saveexec_b64 s[60:61], s[10:11]
	s_cbranch_execz .LBB0_390
	v_cndmask_b32_e64 v58, v46, v47, s[44:45]
	v_cndmask_b32_e64 v46, v32, v33, s[44:45]
	v_lshl_add_u64 v[32:33], s[4:5], 0, v[216:217]
	v_cndmask_b32_e64 v56, v36, v37, s[44:45]
	v_cndmask_b32_e64 v59, v48, v49, s[44:45]
	v_cndmask_b32_e64 v47, v34, v35, s[44:45]
	global_load_dwordx4 v[184:187], v[218:219], off offset:1552
	global_load_dwordx4 v[180:183], v[218:219], off offset:1536
	global_load_dwordx4 v[244:247], v[220:221], off offset:1552
	global_load_dwordx4 v[188:191], v[220:221], off offset:1536
	v_lshl_add_u64 v[32:33], s[8:9], 0, v[216:217]
	v_cndmask_b32_e64 v57, v42, v43, s[44:45]
	v_cndmask_b32_e64 v38, v38, v39, s[44:45]
	v_cndmask_b32_e64 v39, v44, v45, s[44:45]
	s_waitcnt vmcnt(6)
	v_mov_b32_e32 v48, v168
	v_mov_b32_e32 v49, v169
	v_mov_b32_e32 v50, v170
	v_mov_b32_e32 v51, v171
	v_mov_b32_e32 v34, v164
	v_mov_b32_e32 v35, v165
	v_mov_b32_e32 v36, v166
	v_mov_b32_e32 v37, v167
	v_mov_b32_e32 v52, v176
	v_mov_b32_e32 v53, v177
	v_mov_b32_e32 v54, v178
	v_mov_b32_e32 v55, v179
	v_mov_b32_e32 v42, v172
	v_mov_b32_e32 v43, v173
	v_mov_b32_e32 v44, v174
	v_mov_b32_e32 v45, v175
	v_pk_mul_f32 v[32:33], v[30:31], v[36:37]
	v_pk_mul_f32 v[34:35], v[28:29], v[34:35]
	v_pk_mul_f32 v[36:37], v[26:27], v[50:51]
	v_pk_mul_f32 v[42:43], v[42:43], v[46:47]
	v_pk_mul_f32 v[46:47], v[44:45], v[38:39]
	v_pk_mul_f32 v[38:39], v[24:25], v[48:49]
	v_pk_mul_f32 v[44:45], v[52:53], v[56:57]
	v_pk_mul_f32 v[48:49], v[54:55], v[58:59]
	s_and_saveexec_b64 s[62:63], s[42:43]
	s_xor_b64 s[62:63], exec, s[62:63]
	v_pk_add_f32 v[30:31], v[32:33], v[46:47]
	v_pk_add_f32 v[28:29], v[34:35], v[42:43]
	v_pk_add_f32 v[26:27], v[36:37], v[48:49]
	v_pk_add_f32 v[24:25], v[38:39], v[44:45]
	s_andn2_saveexec_b64 s[62:63], s[62:63]
	v_sub_f32_e32 v31, v33, v47
	v_sub_f32_e32 v30, v32, v46
	v_sub_f32_e32 v29, v35, v43
	v_sub_f32_e32 v28, v34, v42
	v_sub_f32_e32 v27, v37, v49
	v_sub_f32_e32 v26, v36, v48
	v_sub_f32_e32 v25, v39, v45
	v_sub_f32_e32 v24, v38, v44
	s_or_b64 exec, exec, s[62:63]

; __device__ __forceinline__ float xpart16(float v, bool oddrow) { auto r = __builtin_amdgcn_permlane16_swap(__float_as_uint(v), __float_as_uint(v), false, false); return __uint_as_float(oddrow ? r[0] : r[1]); }
; __device__ __forceinline__ unsigned cvt_pk_bf16(float lo, float hi) { unsigned r; asm volatile("v_cvt_pk_bf16_f32 %0, %1, %2" : "=v"(r) : "v"(lo), "v"(hi)); return r; }
;     __device__ __forceinline__ void operator()(f32x4 (&acc)[2][2][4][2], const Unit& u, int wr, int wc, int lane) const {
;     ...
;                 for (int bj = 0; bj < 2; ++bj) {
;                     f32x4 v0 = acc[ai][bj][m][0], v1 = acc[ai][bj][m][1];
;                     if (ropesel) {
;                         f32x4 p0, p1;
; #pragma unroll
;                         for (int j = 0; j < 4; ++j) { p0[j] = xpart16(v0[j], (fq & 1) != 0); p1[j] = xpart16(v1[j], (fq & 1) != 0); }
;                         if (rope) {
;                             const f32x4 ca = gld<f32x4>(rc, (unsigned)s * 32u), cb = gld<f32x4>(rc + 4, (unsigned)s * 32u), sa = gld<f32x4>(rs, (unsigned)s * 32u), sb = gld<f32x4>(rs + 4, (unsigned)s * 32u);
;                             if (fq == 0) { v0 = v0 * ca - p0 * sa; v1 = v1 * cb - p1 * sb; }
;                             else { v0 = v0 * ca + p0 * sa; v1 = v1 * cb + p1 * sb; }
;                         }
;                     }
;                     v0 = v0 * osc; v1 = v1 * osc;
;                     u32x4 w; w.x = cvt_pk_bf16(v0[0], v0[1]); w.y = cvt_pk_bf16(v0[2], v0[3]); w.z = cvt_pk_bf16(v1[0], v1[1]); w.w = cvt_pk_bf16(v1[2], v1[3]);
;                     gst<u32x4>(ou + bj * HALF, lo, w);
.LBB0_391:
	s_nop 0
	v_lshl_add_u64 v[32:33], s[58:59], 0, v[96:97]
	v_pk_mul_f32 v[34:35], v[40:41], v[26:27]
	v_pk_mul_f32 v[26:27], v[132:133], v[24:25]
	s_and_b64 vcc, exec, s[46:47]
	v_pk_mul_f32 v[30:31], v[40:41], v[30:31]
	v_pk_mul_f32 v[28:29], v[132:133], v[28:29]
	s_nop 0
	v_cvt_pk_bf16_f32 v24, v28, v29
	v_cvt_pk_bf16_f32 v25, v30, v31
	v_cvt_pk_bf16_f32 v26, v26, v27
	v_cvt_pk_bf16_f32 v27, v34, v35
	global_store_dwordx4 v[32:33], v[24:27], off
	s_cbranch_vccnz .LBB0_399
	s_nop 0
	v_mov_b32_e32 v24, v20
	v_mov_b32_e32 v25, v20
	v_mov_b32_e32 v28, v16
	v_mov_b32_e32 v29, v16
	v_mov_b32_e32 v26, v21
	v_mov_b32_e32 v27, v21
	v_mov_b32_e32 v34, v17
	v_mov_b32_e32 v35, v17
	v_mov_b32_e32 v30, v22
	v_mov_b32_e32 v31, v22
	v_mov_b32_e32 v38, v18
	v_mov_b32_e32 v39, v18
	v_mov_b32_e32 v36, v23
	v_mov_b32_e32 v37, v23
	v_mov_b32_e32 v40, v19
	v_mov_b32_e32 v41, v19
	v_permlane16_swap_b32_e32 v24, v25
	v_permlane16_swap_b32_e32 v28, v29
	v_permlane16_swap_b32_e32 v26, v27
	v_permlane16_swap_b32_e32 v34, v35
	v_permlane16_swap_b32_e32 v30, v31
	v_permlane16_swap_b32_e32 v38, v39
	v_permlane16_swap_b32_e32 v36, v37
	v_permlane16_swap_b32_e32 v40, v41
	s_and_saveexec_b64 s[60:61], s[10:11]
	s_cbranch_execz .LBB0_398
	v_cndmask_b32_e64 v50, v38, v39, s[44:45]
	v_cndmask_b32_e64 v38, v24, v25, s[44:45]
	v_lshl_add_u64 v[24:25], s[4:5], 0, v[216:217]
	v_cndmask_b32_e64 v48, v28, v29, s[44:45]
	v_cndmask_b32_e64 v51, v40, v41, s[44:45]
	v_cndmask_b32_e64 v39, v26, v27, s[44:45]
	v_lshl_add_u64 v[24:25], s[8:9], 0, v[216:217]
	v_cndmask_b32_e64 v49, v34, v35, s[44:45]
	v_cndmask_b32_e64 v30, v30, v31, s[44:45]
	v_cndmask_b32_e64 v31, v36, v37, s[44:45]
	v_mov_b32_e32 v40, v168
	v_mov_b32_e32 v41, v169
	v_mov_b32_e32 v42, v170
	v_mov_b32_e32 v43, v171
	v_mov_b32_e32 v26, v164
	v_mov_b32_e32 v27, v165
	v_mov_b32_e32 v28, v166
	v_mov_b32_e32 v29, v167
	v_mov_b32_e32 v44, v176
	v_mov_b32_e32 v45, v177
	v_mov_b32_e32 v46, v178
	v_mov_b32_e32 v47, v179
	v_mov_b32_e32 v34, v172
	v_mov_b32_e32 v35, v173
	v_mov_b32_e32 v36, v174
	v_mov_b32_e32 v37, v175
	v_pk_mul_f32 v[24:25], v[22:23], v[28:29]
	v_pk_mul_f32 v[26:27], v[20:21], v[26:27]
	v_pk_mul_f32 v[28:29], v[18:19], v[42:43]
	v_pk_mul_f32 v[34:35], v[34:35], v[38:39]
	v_pk_mul_f32 v[38:39], v[36:37], v[30:31]
	v_pk_mul_f32 v[30:31], v[16:17], v[40:41]
	v_pk_mul_f32 v[36:37], v[44:45], v[48:49]
	v_pk_mul_f32 v[40:41], v[46:47], v[50:51]
	s_and_saveexec_b64 s[62:63], s[42:43]
	s_xor_b64 s[62:63], exec, s[62:63]
	v_pk_add_f32 v[22:23], v[24:25], v[38:39]
	v_pk_add_f32 v[20:21], v[26:27], v[34:35]
	v_pk_add_f32 v[18:19], v[28:29], v[40:41]
	v_pk_add_f32 v[16:17], v[30:31], v[36:37]
	s_andn2_saveexec_b64 s[62:63], s[62:63]
	v_sub_f32_e32 v23, v25, v39
	v_sub_f32_e32 v22, v24, v38
	v_sub_f32_e32 v21, v27, v35
	v_sub_f32_e32 v20, v26, v34
	v_sub_f32_e32 v19, v29, v41
	v_sub_f32_e32 v18, v28, v40
	v_sub_f32_e32 v17, v31, v37
	v_sub_f32_e32 v16, v30, v36
	s_or_b64 exec, exec, s[62:63]

; __device__ __forceinline__ float xpart16(float v, bool oddrow) { auto r = __builtin_amdgcn_permlane16_swap(__float_as_uint(v), __float_as_uint(v), false, false); return __uint_as_float(oddrow ? r[0] : r[1]); }
; __device__ __forceinline__ unsigned cvt_pk_bf16(float lo, float hi) { unsigned r; asm volatile("v_cvt_pk_bf16_f32 %0, %1, %2" : "=v"(r) : "v"(lo), "v"(hi)); return r; }
;     __device__ __forceinline__ void operator()(f32x4 (&acc)[2][2][4][2], const Unit& u, int wr, int wc, int lane) const {
;     ...
;                 for (int bj = 0; bj < 2; ++bj) {
;                     f32x4 v0 = acc[ai][bj][m][0], v1 = acc[ai][bj][m][1];
;                     if (ropesel) {
;                         f32x4 p0, p1;
; #pragma unroll
;                         for (int j = 0; j < 4; ++j) { p0[j] = xpart16(v0[j], (fq & 1) != 0); p1[j] = xpart16(v1[j], (fq & 1) != 0); }
;                         if (rope) {
;                             const f32x4 ca = gld<f32x4>(rc, (unsigned)s * 32u), cb = gld<f32x4>(rc + 4, (unsigned)s * 32u), sa = gld<f32x4>(rs, (unsigned)s * 32u), sb = gld<f32x4>(rs + 4, (unsigned)s * 32u);
;                             if (fq == 0) { v0 = v0 * ca - p0 * sa; v1 = v1 * cb - p1 * sb; }
;                             else { v0 = v0 * ca + p0 * sa; v1 = v1 * cb + p1 * sb; }
;                         }
;                     }
;                     v0 = v0 * osc; v1 = v1 * osc;
;                     u32x4 w; w.x = cvt_pk_bf16(v0[0], v0[1]); w.y = cvt_pk_bf16(v0[2], v0[3]); w.z = cvt_pk_bf16(v1[0], v1[1]); w.w = cvt_pk_bf16(v1[2], v1[3]);
;                     gst<u32x4>(ou + bj * HALF, lo, w);
.LBB0_399:
	s_nop 0
	v_mov_b32_e32 v24, v132
	v_mov_b32_e32 v25, v132
	v_pk_mul_f32 v[26:27], v[24:25], v[18:19]
	v_pk_mul_f32 v[18:19], v[132:133], v[16:17]
	s_and_b64 vcc, exec, s[46:47]
	v_pk_mul_f32 v[22:23], v[24:25], v[22:23]
	v_pk_mul_f32 v[20:21], v[132:133], v[20:21]
	s_nop 0
	v_cvt_pk_bf16_f32 v16, v20, v21
	v_cvt_pk_bf16_f32 v17, v22, v23
	v_cvt_pk_bf16_f32 v18, v18, v19
	v_cvt_pk_bf16_f32 v19, v26, v27
	global_store_dwordx4 v[32:33], v[16:19], off offset:256
	s_cbranch_vccnz .LBB0_407
	s_nop 0
	v_mov_b32_e32 v16, v12
	v_mov_b32_e32 v17, v12
	v_mov_b32_e32 v20, v8
	v_mov_b32_e32 v21, v8
	v_mov_b32_e32 v18, v13
	v_mov_b32_e32 v19, v13
	v_mov_b32_e32 v26, v9
	v_mov_b32_e32 v27, v9
	v_mov_b32_e32 v22, v14
	v_mov_b32_e32 v23, v14
	v_mov_b32_e32 v30, v10
	v_mov_b32_e32 v31, v10
	v_mov_b32_e32 v28, v15
	v_mov_b32_e32 v29, v15
	v_mov_b32_e32 v32, v11
	v_mov_b32_e32 v33, v11
	v_permlane16_swap_b32_e32 v16, v17
	v_permlane16_swap_b32_e32 v20, v21
	v_permlane16_swap_b32_e32 v18, v19
	v_permlane16_swap_b32_e32 v26, v27
	v_permlane16_swap_b32_e32 v22, v23
	v_permlane16_swap_b32_e32 v30, v31
	v_permlane16_swap_b32_e32 v28, v29
	v_permlane16_swap_b32_e32 v32, v33
	s_and_saveexec_b64 s[60:61], s[10:11]
	s_cbranch_execz .LBB0_406
	v_cndmask_b32_e64 v42, v30, v31, s[44:45]
	v_cndmask_b32_e64 v30, v16, v17, s[44:45]
	v_lshl_add_u64 v[16:17], s[4:5], 0, v[216:217]
	v_cndmask_b32_e64 v40, v20, v21, s[44:45]
	v_cndmask_b32_e64 v43, v32, v33, s[44:45]
	v_cndmask_b32_e64 v31, v18, v19, s[44:45]
	v_lshl_add_u64 v[16:17], s[8:9], 0, v[216:217]
	v_cndmask_b32_e64 v41, v26, v27, s[44:45]
	v_cndmask_b32_e64 v22, v22, v23, s[44:45]
	v_cndmask_b32_e64 v23, v28, v29, s[44:45]
	s_waitcnt vmcnt(2)
	v_mov_b32_e32 v32, v184
	v_mov_b32_e32 v33, v185
	v_mov_b32_e32 v34, v186
	v_mov_b32_e32 v35, v187
	v_mov_b32_e32 v18, v180
	v_mov_b32_e32 v19, v181
	v_mov_b32_e32 v20, v182
	v_mov_b32_e32 v21, v183
	v_mov_b32_e32 v36, v244
	v_mov_b32_e32 v37, v245
	v_mov_b32_e32 v38, v246
	v_mov_b32_e32 v39, v247
	v_mov_b32_e32 v26, v188
	v_mov_b32_e32 v27, v189
	v_mov_b32_e32 v28, v190
	v_mov_b32_e32 v29, v191
	v_pk_mul_f32 v[16:17], v[14:15], v[20:21]
	v_pk_mul_f32 v[18:19], v[12:13], v[18:19]
	v_pk_mul_f32 v[20:21], v[10:11], v[34:35]
	v_pk_mul_f32 v[26:27], v[26:27], v[30:31]
	v_pk_mul_f32 v[30:31], v[28:29], v[22:23]
	v_pk_mul_f32 v[22:23], v[8:9], v[32:33]
	v_pk_mul_f32 v[28:29], v[36:37], v[40:41]
	v_pk_mul_f32 v[32:33], v[38:39], v[42:43]
	s_and_saveexec_b64 s[62:63], s[42:43]
	s_xor_b64 s[62:63], exec, s[62:63]
	v_pk_add_f32 v[14:15], v[16:17], v[30:31]
	v_pk_add_f32 v[12:13], v[18:19], v[26:27]
	v_pk_add_f32 v[10:11], v[20:21], v[32:33]
	v_pk_add_f32 v[8:9], v[22:23], v[28:29]
	s_andn2_saveexec_b64 s[62:63], s[62:63]
	v_sub_f32_e32 v15, v17, v31
	v_sub_f32_e32 v14, v16, v30
	v_sub_f32_e32 v13, v19, v27
	v_sub_f32_e32 v12, v18, v26
	v_sub_f32_e32 v11, v21, v33
	v_sub_f32_e32 v10, v20, v32
	v_sub_f32_e32 v9, v23, v29
	v_sub_f32_e32 v8, v22, v28
	s_or_b64 exec, exec, s[62:63]

; __device__ __forceinline__ float xpart16(float v, bool oddrow) { auto r = __builtin_amdgcn_permlane16_swap(__float_as_uint(v), __float_as_uint(v), false, false); return __uint_as_float(oddrow ? r[0] : r[1]); }
; __device__ __forceinline__ unsigned cvt_pk_bf16(float lo, float hi) { unsigned r; asm volatile("v_cvt_pk_bf16_f32 %0, %1, %2" : "=v"(r) : "v"(lo), "v"(hi)); return r; }
;     __device__ __forceinline__ void operator()(f32x4 (&acc)[2][2][4][2], const Unit& u, int wr, int wc, int lane) const {
;     ...
;                 for (int bj = 0; bj < 2; ++bj) {
;                     f32x4 v0 = acc[ai][bj][m][0], v1 = acc[ai][bj][m][1];
;                     if (ropesel) {
;                         f32x4 p0, p1;
; #pragma unroll
;                         for (int j = 0; j < 4; ++j) { p0[j] = xpart16(v0[j], (fq & 1) != 0); p1[j] = xpart16(v1[j], (fq & 1) != 0); }
;                         if (rope) {
;                             const f32x4 ca = gld<f32x4>(rc, (unsigned)s * 32u), cb = gld<f32x4>(rc + 4, (unsigned)s * 32u), sa = gld<f32x4>(rs, (unsigned)s * 32u), sb = gld<f32x4>(rs + 4, (unsigned)s * 32u);
;                             if (fq == 0) { v0 = v0 * ca - p0 * sa; v1 = v1 * cb - p1 * sb; }
;                             else { v0 = v0 * ca + p0 * sa; v1 = v1 * cb + p1 * sb; }
;                         }
;                     }
;                     v0 = v0 * osc; v1 = v1 * osc;
;                     u32x4 w; w.x = cvt_pk_bf16(v0[0], v0[1]); w.y = cvt_pk_bf16(v0[2], v0[3]); w.z = cvt_pk_bf16(v1[0], v1[1]); w.w = cvt_pk_bf16(v1[2], v1[3]);
;                     gst<u32x4>(ou + bj * HALF, lo, w);
.LBB0_407:
	s_mov_b32 s60, 0xf800000
	v_lshl_add_u64 v[16:17], s[58:59], 0, v[80:81]
	v_pk_mul_f32 v[18:19], v[24:25], v[10:11]
	v_pk_mul_f32 v[10:11], v[132:133], v[8:9]
	s_and_b64 vcc, exec, s[46:47]
	v_pk_mul_f32 v[14:15], v[24:25], v[14:15]
	v_pk_mul_f32 v[12:13], v[132:133], v[12:13]
	s_nop 0
	v_cvt_pk_bf16_f32 v8, v12, v13
	v_cvt_pk_bf16_f32 v9, v14, v15
	v_cvt_pk_bf16_f32 v10, v10, v11
	v_cvt_pk_bf16_f32 v11, v18, v19
	global_store_dwordx4 v[16:17], v[8:11], off
	s_cbranch_vccnz .LBB0_415
	s_nop 0
	v_mov_b32_e32 v8, v4
	v_mov_b32_e32 v9, v4
	v_mov_b32_e32 v12, v0
	v_mov_b32_e32 v13, v0
	v_mov_b32_e32 v10, v5
	v_mov_b32_e32 v11, v5
	v_mov_b32_e32 v18, v1
	v_mov_b32_e32 v19, v1
	v_mov_b32_e32 v14, v6
	v_mov_b32_e32 v15, v6
	v_mov_b32_e32 v22, v2
	v_mov_b32_e32 v23, v2
	v_mov_b32_e32 v20, v7
	v_mov_b32_e32 v21, v7
	v_mov_b32_e32 v24, v3
	v_mov_b32_e32 v25, v3
	v_permlane16_swap_b32_e32 v8, v9
	v_permlane16_swap_b32_e32 v12, v13
	v_permlane16_swap_b32_e32 v10, v11
	v_permlane16_swap_b32_e32 v18, v19
	v_permlane16_swap_b32_e32 v14, v15
	v_permlane16_swap_b32_e32 v22, v23
	v_permlane16_swap_b32_e32 v20, v21
	v_permlane16_swap_b32_e32 v24, v25
	s_and_saveexec_b64 s[46:47], s[10:11]
	s_cbranch_execz .LBB0_414
	v_cndmask_b32_e64 v34, v22, v23, s[44:45]
	v_cndmask_b32_e64 v22, v8, v9, s[44:45]
	v_lshl_add_u64 v[8:9], s[4:5], 0, v[216:217]
	v_cndmask_b32_e64 v32, v12, v13, s[44:45]
	v_cndmask_b32_e64 v35, v24, v25, s[44:45]
	v_cndmask_b32_e64 v23, v10, v11, s[44:45]
	v_lshl_add_u64 v[8:9], s[8:9], 0, v[216:217]
	v_cndmask_b32_e64 v33, v18, v19, s[44:45]
	v_cndmask_b32_e64 v14, v14, v15, s[44:45]
	v_cndmask_b32_e64 v15, v20, v21, s[44:45]
	v_mov_b32_e32 v24, v184
	v_mov_b32_e32 v25, v185
	v_mov_b32_e32 v26, v186
	v_mov_b32_e32 v27, v187
	v_mov_b32_e32 v10, v180
	v_mov_b32_e32 v11, v181
	v_mov_b32_e32 v12, v182
	v_mov_b32_e32 v13, v183
	v_mov_b32_e32 v28, v244
	v_mov_b32_e32 v29, v245
	v_mov_b32_e32 v30, v246
	v_mov_b32_e32 v31, v247
	v_mov_b32_e32 v18, v188
	v_mov_b32_e32 v19, v189
	v_mov_b32_e32 v20, v190
	v_mov_b32_e32 v21, v191
	v_pk_mul_f32 v[8:9], v[6:7], v[12:13]
	v_pk_mul_f32 v[10:11], v[4:5], v[10:11]
	v_pk_mul_f32 v[12:13], v[2:3], v[26:27]
	v_pk_mul_f32 v[18:19], v[18:19], v[22:23]
	v_pk_mul_f32 v[22:23], v[20:21], v[14:15]
	v_pk_mul_f32 v[14:15], v[0:1], v[24:25]
	v_pk_mul_f32 v[20:21], v[28:29], v[32:33]
	v_pk_mul_f32 v[24:25], v[30:31], v[34:35]
	s_and_saveexec_b64 s[10:11], s[42:43]
	s_xor_b64 s[10:11], exec, s[10:11]
	v_pk_add_f32 v[6:7], v[8:9], v[22:23]
	v_pk_add_f32 v[4:5], v[10:11], v[18:19]
	v_pk_add_f32 v[2:3], v[12:13], v[24:25]
	v_pk_add_f32 v[0:1], v[14:15], v[20:21]
	s_andn2_saveexec_b64 s[10:11], s[10:11]
	v_sub_f32_e32 v7, v9, v23
	v_sub_f32_e32 v6, v8, v22
	v_sub_f32_e32 v5, v11, v19
	v_sub_f32_e32 v4, v10, v18
	v_sub_f32_e32 v3, v13, v25
	v_sub_f32_e32 v2, v12, v24
	v_sub_f32_e32 v1, v15, v21
	v_sub_f32_e32 v0, v14, v20
	s_or_b64 exec, exec, s[10:11]

;     __device__ __forceinline__ void run(const f32x4 (&v)[2][2][4][2], const Unit& u, int wr, int wc, int lane) const {
;     ...
;             __builtin_amdgcn_fence(__ATOMIC_ACQUIRE, "agent");
;         }
;         asm volatile("s_waitcnt vmcnt(0) lgkmcnt(0)" ::: "memory"); __builtin_amdgcn_s_barrier(); asm volatile("" ::: "memory");
;         if (lane < 32) {
;             const unsigned long long* slot = (const unsigned long long*)xbuf + (size_t)(u.pm * BM + row) * 4; float mt[4], m2[4]; float ms = 0.f;
; #pragma unroll
;             for (int t = 0; t < 4; ++t) { const unsigned long long w = __hip_atomic_load(slot + t, __ATOMIC_RELAXED, __HIP_MEMORY_SCOPE_AGENT); mt[t] = __uint_as_float((unsigned)w); m2[t] = __uint_as_float((unsigned)(w >> 32)); ms += mt[t]; }
;             const float mean = ms * 0.25f; float q = 0.f;
; #pragma unroll
;             for (int t = 0; t < 4; ++t) { const float dm = mt[t] - mean; q += m2[t] + 256.0f * dm * dm; }
;             S[row] = (f32x2){mean, 1.0f / sqrtf(q * (1.0f / 1024.0f) + LN_EPS)};
.LBB0_1206:
.LBB0_1207:
	s_waitcnt vmcnt(0) lgkmcnt(0)
	s_barrier
	s_and_saveexec_b64 s[44:45], s[42:43]
	s_cbranch_execz .LBB0_1209
	v_lshlrev_b64 v[128:129], 5, v[128:129]
	v_lshl_add_u64 v[128:129], s[22:23], 0, v[128:129]
	flat_load_dwordx2 v[132:133], v[128:129] sc1
	flat_load_dwordx2 v[134:135], v[128:129] offset:8 sc1
	flat_load_dwordx2 v[136:137], v[128:129] offset:16 sc1
	flat_load_dwordx2 v[138:139], v[128:129] offset:24 sc1
	s_mov_b32 s39, 0xf800000
	v_lshl_add_u32 v130, v130, 3, 0
	v_add_u32_e32 v130, 0x22400, v130
	s_waitcnt vmcnt(0) lgkmcnt(0)
	v_add_f32_e32 v131, 0, v132
	v_add_f32_e32 v131, v131, v134
	v_add_f32_e32 v131, v131, v136
	v_add_f32_e32 v129, v131, v138
	v_fmamk_f32 v131, v129, 0xbe800000, v132
	v_mul_f32_e32 v132, 0x43800000, v131
	v_fmac_f32_e32 v133, v131, v132
	v_fmamk_f32 v132, v129, 0xbe800000, v134
	v_add_f32_e32 v131, 0, v133
	v_mul_f32_e32 v133, 0x43800000, v132
	v_fmac_f32_e32 v135, v132, v133
	v_fmamk_f32 v132, v129, 0xbe800000, v136
	v_mul_f32_e32 v128, 0x3e800000, v129
	v_mul_f32_e32 v133, 0x43800000, v132
	v_fmamk_f32 v129, v129, 0xbe800000, v138
	v_add_f32_e32 v131, v135, v131
	v_fmac_f32_e32 v137, v132, v133
	v_mul_f32_e32 v132, 0x43800000, v129
	v_add_f32_e32 v131, v137, v131
	v_fmac_f32_e32 v139, v129, v132
	v_add_f32_e32 v129, v139, v131
	v_mov_b32_e32 v131, 0x3727c5ac
	v_fmamk_f32 v129, v129, 0x3a800000, v131
	v_cmp_gt_f32_e32 vcc, s39, v129
	v_mul_f32_e32 v131, 0x4f800000, v129
	s_nop 0
	v_cndmask_b32_e32 v129, v129, v131, vcc
	v_sqrt_f32_e32 v131, v129
	s_nop 0
	v_add_u32_e32 v132, -1, v131
	v_fma_f32 v133, -v132, v131, v129
	v_cmp_ge_f32_e64 s[42:43], 0, v133
	v_add_u32_e32 v133, 1, v131
	s_nop 0
	v_cndmask_b32_e64 v132, v131, v132, s[42:43]
	v_fma_f32 v131, -v133, v131, v129
	v_cmp_lt_f32_e64 s[42:43], 0, v131
	s_nop 1
	v_cndmask_b32_e64 v131, v132, v133, s[42:43]
	v_mul_f32_e32 v132, 0x37800000, v131
	v_cndmask_b32_e32 v131, v131, v132, vcc
	v_cmp_class_f32_e32 vcc, v129, v233
	s_nop 1
	v_cndmask_b32_e32 v129, v131, v129, vcc
	v_div_scale_f32 v131, s[42:43], v129, v129, 1.0
	v_rcp_f32_e32 v132, v131
	s_nop 0
	v_fma_f32 v133, -v131, v132, 1.0
	v_fmac_f32_e32 v132, v133, v132
	v_div_scale_f32 v133, vcc, 1.0, v129, 1.0
	v_mul_f32_e32 v134, v133, v132
	v_fma_f32 v135, -v131, v134, v133
	v_fmac_f32_e32 v134, v135, v132
	v_fma_f32 v131, -v131, v134, v133
	v_div_fmas_f32 v131, v131, v132, v134
	v_div_fixup_f32 v129, v131, v129, 1.0
	ds_write_b64 v130, v[128:129]

; __device__ __forceinline__ unsigned xb_ld(unsigned* p)              { return __hip_atomic_load(p, __ATOMIC_RELAXED, __HIP_MEMORY_SCOPE_AGENT); }
; __device__ __forceinline__ unsigned xb_add(unsigned* p, unsigned v) { return __hip_atomic_fetch_add(p, v, __ATOMIC_RELAXED, __HIP_MEMORY_SCOPE_AGENT); }
; #define XB_SPIN(cond, bar) do { unsigned _sp = 0; while (cond) { __builtin_amdgcn_s_sleep(1); \
;     if ((++_sp & 255u) == 0u) { if (xb_ld(&(bar)[XB_TMO])) break; if (_sp > XB_SPIN_CAP) { atomicAdd(&(bar)[XB_TMO], 1u); break; } } } } while (0)
; __device__ __forceinline__ void xcd_barrier(const XcdBarrier& b) {
;     ...
;             const unsigned og = xb_add(&bar[XB_TOP], 1u);
;             const unsigned tg = og / nx;
;             if (og + 1u == (tg + 1u) * nx) xb_add(&bar[XB_TOPGEN], 1u);
;             else XB_SPIN(xb_ld(&bar[XB_TOPGEN]) == tg, bar);
;             __builtin_amdgcn_fence(__ATOMIC_ACQUIRE, "agent");
;             xb_add(&bar[XB_XGEN(b.x)], 1u);
.LBB0_1358:
	s_or_b64 exec, exec, s[4:5]
	s_mov_b64 s[4:5], exec
	v_mbcnt_lo_u32_b32 v0, s4, 0
	v_mbcnt_hi_u32_b32 v0, s5, v0
	v_cmp_eq_u32_e32 vcc, 0, v0
	s_waitcnt vmcnt(0)
	s_and_saveexec_b64 s[8:9], vcc
	s_cbranch_execnz .LBB0_1359
	s_getpc_b64 s[98:99]
